# gemm_mid stages: previous block's epilogue VALU/stores interleaved between the current block's MFMAs (static variants per pending-block kind)
# baseline (speedup 1.0000x reference)
.Lkv_loop:
	s_waitcnt vmcnt(11)
	ds_write_b128 v246, v[224:227] offset:8704
	s_add_u32 s0, s5, -1
	s_min_u32 s0, s25, s0
	s_mul_hi_u32 s1, s0, 0xaaaaaaab
	s_lshr_b32 s1, s1, 4
	s_mul_i32 s1, s1, 24
	s_sub_u32 s0, s0, s1
	s_lshl_b32 s0, s0, 13
	s_add_u32 s10, s8, s0
	s_addc_u32 s11, s9, 0
	global_load_dwordx4 v[224:227], v247, s[10:11]
	s_add_u32 s25, s25, 1
	s_mul_hi_u32 s1, s4, 0xaaaaaaab
	s_lshr_b32 s1, s1, 4
	s_mul_i32 s1, s1, 24
	s_sub_u32 s0, s4, s1
	s_lshr_b32 s1, s0, 2
	s_mul_i32 s1, s1, 4352
	s_add_u32 s1, s1, s18
	s_and_b32 s0, s0, 3
	s_lshl_b32 s32, s0, 6
	s_mul_i32 s54, s1, 192
	s_add_u32 s54, s54, s32
	s_add_u32 s54, s54, 0x12f1d000
	s_lshl_b32 s55, s1, 7
	s_add_u32 s55, s55, s32
	s_add_u32 s55, s55, 0x1555cf80
	s_cmp_lt_u32 s0, 2
	s_cselect_b32 s54, s54, s55
	s_cselect_b32 s17, 0, 1
	s_add_u32 s14, s50, s54
	s_addc_u32 s15, s51, 0
	ds_read_b128 v[188:191], v248 offset:0
	ds_read_b128 v[192:195], v248 offset:32
	ds_read_b128 v[196:199], v248 offset:64
	ds_read_b128 v[200:203], v248 offset:96
	ds_read_b128 v[204:207], v248 offset:128
	ds_read_b128 v[208:211], v248 offset:160
	ds_read_b128 v[212:215], v248 offset:192
	ds_read_b128 v[216:219], v248 offset:224
	s_cmp_eq_u32 s16, 2
	s_cbranch_scc0 .Lkv_ep0
	s_waitcnt lgkmcnt(7)
	v_mfma_f32_32x32x16_bf16 v[0:15], v[188:191], v[96:99], 0
	global_load_dword v156, v243, s[26:27]
	s_waitcnt lgkmcnt(6)
	v_mfma_f32_32x32x16_bf16 v[0:15], v[192:195], v[100:103], v[0:15]
	global_load_dword v157, v243, s[26:27]
	s_waitcnt lgkmcnt(5)
	v_mfma_f32_32x32x16_bf16 v[0:15], v[196:199], v[104:107], v[0:15]
	s_waitcnt lgkmcnt(4)
	v_mfma_f32_32x32x16_bf16 v[0:15], v[200:203], v[108:111], v[0:15]
	s_waitcnt lgkmcnt(3)
	v_mfma_f32_32x32x16_bf16 v[0:15], v[204:207], v[112:115], v[0:15]
	s_waitcnt lgkmcnt(2)
	v_mfma_f32_32x32x16_bf16 v[0:15], v[208:211], v[116:119], v[0:15]
	s_waitcnt lgkmcnt(1)
	v_mfma_f32_32x32x16_bf16 v[0:15], v[212:215], v[120:123], v[0:15]
	s_waitcnt lgkmcnt(0)
	v_mfma_f32_32x32x16_bf16 v[0:15], v[216:219], v[124:127], v[0:15]
	s_branch .Lkv_ex0
.Lkv_ep0:
	s_waitcnt lgkmcnt(7)
	v_mfma_f32_32x32x16_bf16 v[0:15], v[188:191], v[96:99], 0
	v_mul_f32_e32 v16, v16, v155
	v_mul_f32_e32 v17, v17, v155
	v_mul_f32_e32 v18, v18, v155
	v_mul_f32_e32 v19, v19, v155
	v_mul_f32_e32 v20, v20, v155
	s_waitcnt lgkmcnt(6)
	v_mfma_f32_32x32x16_bf16 v[0:15], v[192:195], v[100:103], v[0:15]
	v_mul_f32_e32 v21, v21, v155
	v_mul_f32_e32 v22, v22, v155
	v_mul_f32_e32 v23, v23, v155
	v_mul_f32_e32 v24, v24, v155
	v_mul_f32_e32 v25, v25, v155
	s_waitcnt lgkmcnt(5)
	v_mfma_f32_32x32x16_bf16 v[0:15], v[196:199], v[104:107], v[0:15]
	v_mul_f32_e32 v26, v26, v155
	v_mul_f32_e32 v27, v27, v155
	v_mul_f32_e32 v28, v28, v155
	v_mul_f32_e32 v29, v29, v155
	v_mul_f32_e32 v30, v30, v155
	s_waitcnt lgkmcnt(4)
	v_mfma_f32_32x32x16_bf16 v[0:15], v[200:203], v[108:111], v[0:15]
	v_mul_f32_e32 v31, v31, v155
	v_cvt_pk_bf16_f32 v144, v16, v17
	v_cvt_pk_bf16_f32 v145, v18, v19
	v_cvt_pk_bf16_f32 v148, v20, v21
	v_cvt_pk_bf16_f32 v149, v22, v23
	s_waitcnt lgkmcnt(3)
	v_mfma_f32_32x32x16_bf16 v[0:15], v[204:207], v[112:115], v[0:15]
	v_cvt_pk_bf16_f32 v146, v24, v25
	v_cvt_pk_bf16_f32 v147, v26, v27
	v_cvt_pk_bf16_f32 v150, v28, v29
	v_cvt_pk_bf16_f32 v151, v30, v31
	s_nop 1
	s_waitcnt lgkmcnt(2)
	v_mfma_f32_32x32x16_bf16 v[0:15], v[208:211], v[116:119], v[0:15]
	v_permlane32_swap_b32_e32 v144, v146
	v_permlane32_swap_b32_e32 v145, v147
	v_permlane32_swap_b32_e32 v148, v150
	v_permlane32_swap_b32_e32 v149, v151
	global_store_dwordx4 v158, v[144:147], s[12:13]
	s_waitcnt lgkmcnt(1)
	v_mfma_f32_32x32x16_bf16 v[0:15], v[212:215], v[120:123], v[0:15]
	global_store_dwordx4 v158, v[148:151], s[12:13] offset:16
	s_waitcnt lgkmcnt(0)
	v_mfma_f32_32x32x16_bf16 v[0:15], v[216:219], v[124:127], v[0:15]
.Lkv_ex0:
	v_mov_b32_e32 v155, v154
	s_mov_b64 s[12:13], s[14:15]
	s_mov_b32 s16, s17
	s_cmp_lg_u32 s17, 0
	s_cselect_b64 s[68:69], -1, 0
	v_cndmask_b32_e64 v158, v244, v245, s[68:69]
	s_add_u32 s4, s4, 1
	s_waitcnt lgkmcnt(0)
	s_barrier
	s_cmp_ge_u32 s4, s5
	s_cbranch_scc1 .Lkv_drain0
	s_cmp_lg_u32 s4, s6
	s_cbranch_scc1 .Lkv_ns0
	s_nop 7
	s_nop 7
	s_nop 7
	s_nop 7
	v_mov_b32_e32 v96, v48
	v_mov_b32_e32 v97, v49
	v_mov_b32_e32 v98, v50
	v_mov_b32_e32 v99, v51
	v_mov_b32_e32 v100, v52
	v_mov_b32_e32 v101, v53
	v_mov_b32_e32 v102, v54
	v_mov_b32_e32 v103, v55
	v_mov_b32_e32 v104, v56
	v_mov_b32_e32 v105, v57
	v_mov_b32_e32 v106, v58
	v_mov_b32_e32 v107, v59
	v_mov_b32_e32 v108, v60
	v_mov_b32_e32 v109, v61
	v_mov_b32_e32 v110, v62
	v_mov_b32_e32 v111, v63
	v_mov_b32_e32 v112, v64
	v_mov_b32_e32 v113, v65
	v_mov_b32_e32 v114, v66
	v_mov_b32_e32 v115, v67
	v_mov_b32_e32 v116, v68
	v_mov_b32_e32 v117, v69
	v_mov_b32_e32 v118, v70
	v_mov_b32_e32 v119, v71
	v_mov_b32_e32 v120, v72
	v_mov_b32_e32 v121, v73
	v_mov_b32_e32 v122, v74
	v_mov_b32_e32 v123, v75
	v_mov_b32_e32 v124, v76
	v_mov_b32_e32 v125, v77
	v_mov_b32_e32 v126, v78
	v_mov_b32_e32 v127, v79
	v_mov_b32_e32 v154, v153
	s_mov_b32 s18, s19
	s_mov_b32 s6, s5
.Lkv_ns0:
	s_waitcnt vmcnt(11)
	ds_write_b128 v246, v[228:231] offset:0
	s_add_u32 s0, s5, -1
	s_min_u32 s0, s25, s0
	s_mul_hi_u32 s1, s0, 0xaaaaaaab
	s_lshr_b32 s1, s1, 4
	s_mul_i32 s1, s1, 24
	s_sub_u32 s0, s0, s1
	s_lshl_b32 s0, s0, 13
	s_add_u32 s10, s8, s0
	s_addc_u32 s11, s9, 0
	global_load_dwordx4 v[228:231], v247, s[10:11]
	s_add_u32 s25, s25, 1
	s_mul_hi_u32 s1, s4, 0xaaaaaaab
	s_lshr_b32 s1, s1, 4
	s_mul_i32 s1, s1, 24
	s_sub_u32 s0, s4, s1
	s_lshr_b32 s1, s0, 2
	s_mul_i32 s1, s1, 4352
	s_add_u32 s1, s1, s18
	s_and_b32 s0, s0, 3
	s_lshl_b32 s32, s0, 6
	s_mul_i32 s54, s1, 192
	s_add_u32 s54, s54, s32
	s_add_u32 s54, s54, 0x12f1d000
	s_lshl_b32 s55, s1, 7
	s_add_u32 s55, s55, s32
	s_add_u32 s55, s55, 0x1555cf80
	s_cmp_lt_u32 s0, 2
	s_cselect_b32 s54, s54, s55
	s_cselect_b32 s17, 0, 1
	s_add_u32 s14, s50, s54
	s_addc_u32 s15, s51, 0
	ds_read_b128 v[188:191], v248 offset:8704
	ds_read_b128 v[192:195], v248 offset:8736
	ds_read_b128 v[196:199], v248 offset:8768
	ds_read_b128 v[200:203], v248 offset:8800
	ds_read_b128 v[204:207], v248 offset:8832
	ds_read_b128 v[208:211], v248 offset:8864
	ds_read_b128 v[212:215], v248 offset:8896
	ds_read_b128 v[216:219], v248 offset:8928
	s_cmp_eq_u32 s16, 2
	s_cbranch_scc0 .Lkv_ep1
	s_waitcnt lgkmcnt(7)
	v_mfma_f32_32x32x16_bf16 v[16:31], v[188:191], v[96:99], 0
	global_load_dword v156, v243, s[26:27]
	s_waitcnt lgkmcnt(6)
	v_mfma_f32_32x32x16_bf16 v[16:31], v[192:195], v[100:103], v[16:31]
	global_load_dword v157, v243, s[26:27]
	s_waitcnt lgkmcnt(5)
	v_mfma_f32_32x32x16_bf16 v[16:31], v[196:199], v[104:107], v[16:31]
	s_waitcnt lgkmcnt(4)
	v_mfma_f32_32x32x16_bf16 v[16:31], v[200:203], v[108:111], v[16:31]
	s_waitcnt lgkmcnt(3)
	v_mfma_f32_32x32x16_bf16 v[16:31], v[204:207], v[112:115], v[16:31]
	s_waitcnt lgkmcnt(2)
	v_mfma_f32_32x32x16_bf16 v[16:31], v[208:211], v[116:119], v[16:31]
	s_waitcnt lgkmcnt(1)
	v_mfma_f32_32x32x16_bf16 v[16:31], v[212:215], v[120:123], v[16:31]
	s_waitcnt lgkmcnt(0)
	v_mfma_f32_32x32x16_bf16 v[16:31], v[216:219], v[124:127], v[16:31]
	s_branch .Lkv_ex1
.Lkv_ep1:
	s_waitcnt lgkmcnt(7)
	v_mfma_f32_32x32x16_bf16 v[16:31], v[188:191], v[96:99], 0
	v_mul_f32_e32 v0, v0, v155
	v_mul_f32_e32 v1, v1, v155
	v_mul_f32_e32 v2, v2, v155
	v_mul_f32_e32 v3, v3, v155
	v_mul_f32_e32 v4, v4, v155
	s_waitcnt lgkmcnt(6)
	v_mfma_f32_32x32x16_bf16 v[16:31], v[192:195], v[100:103], v[16:31]
	v_mul_f32_e32 v5, v5, v155
	v_mul_f32_e32 v6, v6, v155
	v_mul_f32_e32 v7, v7, v155
	v_mul_f32_e32 v8, v8, v155
	v_mul_f32_e32 v9, v9, v155
	s_waitcnt lgkmcnt(5)
	v_mfma_f32_32x32x16_bf16 v[16:31], v[196:199], v[104:107], v[16:31]
	v_mul_f32_e32 v10, v10, v155
	v_mul_f32_e32 v11, v11, v155
	v_mul_f32_e32 v12, v12, v155
	v_mul_f32_e32 v13, v13, v155
	v_mul_f32_e32 v14, v14, v155
	s_waitcnt lgkmcnt(4)
	v_mfma_f32_32x32x16_bf16 v[16:31], v[200:203], v[108:111], v[16:31]
	v_mul_f32_e32 v15, v15, v155
	v_cvt_pk_bf16_f32 v144, v0, v1
	v_cvt_pk_bf16_f32 v145, v2, v3
	v_cvt_pk_bf16_f32 v148, v4, v5
	v_cvt_pk_bf16_f32 v149, v6, v7
	s_waitcnt lgkmcnt(3)
	v_mfma_f32_32x32x16_bf16 v[16:31], v[204:207], v[112:115], v[16:31]
	v_cvt_pk_bf16_f32 v146, v8, v9
	v_cvt_pk_bf16_f32 v147, v10, v11
	v_cvt_pk_bf16_f32 v150, v12, v13
	v_cvt_pk_bf16_f32 v151, v14, v15
	s_nop 1
	s_waitcnt lgkmcnt(2)
	v_mfma_f32_32x32x16_bf16 v[16:31], v[208:211], v[116:119], v[16:31]
	v_permlane32_swap_b32_e32 v144, v146
	v_permlane32_swap_b32_e32 v145, v147
	v_permlane32_swap_b32_e32 v148, v150
	v_permlane32_swap_b32_e32 v149, v151
	global_store_dwordx4 v158, v[144:147], s[12:13]
	s_waitcnt lgkmcnt(1)
	v_mfma_f32_32x32x16_bf16 v[16:31], v[212:215], v[120:123], v[16:31]
	global_store_dwordx4 v158, v[148:151], s[12:13] offset:16
	s_waitcnt lgkmcnt(0)
	v_mfma_f32_32x32x16_bf16 v[16:31], v[216:219], v[124:127], v[16:31]

.Lkv_ns1:
	s_waitcnt vmcnt(11)
	ds_write_b128 v246, v[238:241] offset:8704
	s_add_u32 s0, s5, -1
	s_min_u32 s0, s25, s0
	s_mul_hi_u32 s1, s0, 0xaaaaaaab
	s_lshr_b32 s1, s1, 4
	s_mul_i32 s1, s1, 24
	s_sub_u32 s0, s0, s1
	s_lshl_b32 s0, s0, 13
	s_add_u32 s10, s8, s0
	s_addc_u32 s11, s9, 0
	global_load_dwordx4 v[238:241], v247, s[10:11]
	s_add_u32 s25, s25, 1
	s_mul_hi_u32 s1, s4, 0xaaaaaaab
	s_lshr_b32 s1, s1, 4
	s_mul_i32 s1, s1, 24
	s_sub_u32 s0, s4, s1
	s_lshr_b32 s1, s0, 2
	s_mul_i32 s1, s1, 4352
	s_add_u32 s1, s1, s18
	s_and_b32 s0, s0, 3
	s_lshl_b32 s32, s0, 6
	s_mul_i32 s54, s1, 192
	s_add_u32 s54, s54, s32
	s_add_u32 s54, s54, 0x12f1d000
	s_lshl_b32 s55, s1, 7
	s_add_u32 s55, s55, s32
	s_add_u32 s55, s55, 0x1555cf80
	s_cmp_lt_u32 s0, 2
	s_cselect_b32 s54, s54, s55
	s_cselect_b32 s17, 0, 1
	s_add_u32 s14, s50, s54
	s_addc_u32 s15, s51, 0
	ds_read_b128 v[188:191], v248 offset:0
	ds_read_b128 v[192:195], v248 offset:32
	ds_read_b128 v[196:199], v248 offset:64
	ds_read_b128 v[200:203], v248 offset:96
	ds_read_b128 v[204:207], v248 offset:128
	ds_read_b128 v[208:211], v248 offset:160
	ds_read_b128 v[212:215], v248 offset:192
	ds_read_b128 v[216:219], v248 offset:224
	s_cmp_eq_u32 s16, 2
	s_cbranch_scc0 .Lkv_ep2
	s_waitcnt lgkmcnt(7)
	v_mfma_f32_32x32x16_bf16 v[0:15], v[188:191], v[96:99], 0
	global_load_dword v156, v243, s[26:27]
	s_waitcnt lgkmcnt(6)
	v_mfma_f32_32x32x16_bf16 v[0:15], v[192:195], v[100:103], v[0:15]
	global_load_dword v157, v243, s[26:27]
	s_waitcnt lgkmcnt(5)
	v_mfma_f32_32x32x16_bf16 v[0:15], v[196:199], v[104:107], v[0:15]
	s_waitcnt lgkmcnt(4)
	v_mfma_f32_32x32x16_bf16 v[0:15], v[200:203], v[108:111], v[0:15]
	s_waitcnt lgkmcnt(3)
	v_mfma_f32_32x32x16_bf16 v[0:15], v[204:207], v[112:115], v[0:15]
	s_waitcnt lgkmcnt(2)
	v_mfma_f32_32x32x16_bf16 v[0:15], v[208:211], v[116:119], v[0:15]
	s_waitcnt lgkmcnt(1)
	v_mfma_f32_32x32x16_bf16 v[0:15], v[212:215], v[120:123], v[0:15]
	s_waitcnt lgkmcnt(0)
	v_mfma_f32_32x32x16_bf16 v[0:15], v[216:219], v[124:127], v[0:15]
	s_branch .Lkv_ex2

.Lkv_ns2:
	s_waitcnt vmcnt(11)
	ds_write_b128 v246, v[220:223] offset:0
	s_add_u32 s0, s5, -1
	s_min_u32 s0, s25, s0
	s_mul_hi_u32 s1, s0, 0xaaaaaaab
	s_lshr_b32 s1, s1, 4
	s_mul_i32 s1, s1, 24
	s_sub_u32 s0, s0, s1
	s_lshl_b32 s0, s0, 13
	s_add_u32 s10, s8, s0
	s_addc_u32 s11, s9, 0
	global_load_dwordx4 v[220:223], v247, s[10:11]
	s_add_u32 s25, s25, 1
	s_mul_hi_u32 s1, s4, 0xaaaaaaab
	s_lshr_b32 s1, s1, 4
	s_mul_i32 s1, s1, 24
	s_sub_u32 s0, s4, s1
	s_lshr_b32 s1, s0, 2
	s_mul_i32 s1, s1, 4352
	s_add_u32 s1, s1, s18
	s_and_b32 s0, s0, 3
	s_lshl_b32 s32, s0, 6
	s_mul_i32 s54, s1, 192
	s_add_u32 s54, s54, s32
	s_add_u32 s54, s54, 0x12f1d000
	s_lshl_b32 s55, s1, 7
	s_add_u32 s55, s55, s32
	s_add_u32 s55, s55, 0x1555cf80
	s_cmp_lt_u32 s0, 2
	s_cselect_b32 s54, s54, s55
	s_cselect_b32 s17, 0, 1
	s_add_u32 s14, s50, s54
	s_addc_u32 s15, s51, 0
	ds_read_b128 v[188:191], v248 offset:8704
	ds_read_b128 v[192:195], v248 offset:8736
	ds_read_b128 v[196:199], v248 offset:8768
	ds_read_b128 v[200:203], v248 offset:8800
	ds_read_b128 v[204:207], v248 offset:8832
	ds_read_b128 v[208:211], v248 offset:8864
	ds_read_b128 v[212:215], v248 offset:8896
	ds_read_b128 v[216:219], v248 offset:8928
	s_cmp_eq_u32 s16, 2
	s_cbranch_scc0 .Lkv_ep3
	s_waitcnt lgkmcnt(7)
	v_mfma_f32_32x32x16_bf16 v[16:31], v[188:191], v[96:99], 0
	global_load_dword v156, v243, s[26:27]
	s_waitcnt lgkmcnt(6)
	v_mfma_f32_32x32x16_bf16 v[16:31], v[192:195], v[100:103], v[16:31]
	global_load_dword v157, v243, s[26:27]
	s_waitcnt lgkmcnt(5)
	v_mfma_f32_32x32x16_bf16 v[16:31], v[196:199], v[104:107], v[16:31]
	s_waitcnt lgkmcnt(4)
	v_mfma_f32_32x32x16_bf16 v[16:31], v[200:203], v[108:111], v[16:31]
	s_waitcnt lgkmcnt(3)
	v_mfma_f32_32x32x16_bf16 v[16:31], v[204:207], v[112:115], v[16:31]
	s_waitcnt lgkmcnt(2)
	v_mfma_f32_32x32x16_bf16 v[16:31], v[208:211], v[116:119], v[16:31]
	s_waitcnt lgkmcnt(1)
	v_mfma_f32_32x32x16_bf16 v[16:31], v[212:215], v[120:123], v[16:31]
	s_waitcnt lgkmcnt(0)
	v_mfma_f32_32x32x16_bf16 v[16:31], v[216:219], v[124:127], v[16:31]
	s_branch .Lkv_ex3

.Lkv_drain0:
	s_nop 7
	s_nop 7
	v_mul_f32_e32 v0, v0, v155
	v_mul_f32_e32 v1, v1, v155
	v_mul_f32_e32 v2, v2, v155
	v_mul_f32_e32 v3, v3, v155
	v_mul_f32_e32 v4, v4, v155
	v_mul_f32_e32 v5, v5, v155
	v_mul_f32_e32 v6, v6, v155
	v_mul_f32_e32 v7, v7, v155
	v_mul_f32_e32 v8, v8, v155
	v_mul_f32_e32 v9, v9, v155
	v_mul_f32_e32 v10, v10, v155
	v_mul_f32_e32 v11, v11, v155
	v_mul_f32_e32 v12, v12, v155
	v_mul_f32_e32 v13, v13, v155
	v_mul_f32_e32 v14, v14, v155
	v_mul_f32_e32 v15, v15, v155
	v_cvt_pk_bf16_f32 v144, v0, v1
	v_cvt_pk_bf16_f32 v145, v2, v3
	v_cvt_pk_bf16_f32 v148, v4, v5
	v_cvt_pk_bf16_f32 v149, v6, v7
	v_cvt_pk_bf16_f32 v146, v8, v9
	v_cvt_pk_bf16_f32 v147, v10, v11
	v_cvt_pk_bf16_f32 v150, v12, v13
	v_cvt_pk_bf16_f32 v151, v14, v15
	s_nop 1
	v_permlane32_swap_b32_e32 v144, v146
	v_permlane32_swap_b32_e32 v145, v147
	v_permlane32_swap_b32_e32 v148, v150
	v_permlane32_swap_b32_e32 v149, v151
	global_store_dwordx4 v158, v[144:147], s[12:13]
	global_store_dwordx4 v158, v[148:151], s[12:13] offset:16
	s_branch .Lkv_done
.Lkv_drain1:
	s_nop 7
	s_nop 7
	v_mul_f32_e32 v16, v16, v155
	v_mul_f32_e32 v17, v17, v155
	v_mul_f32_e32 v18, v18, v155
	v_mul_f32_e32 v19, v19, v155
	v_mul_f32_e32 v20, v20, v155
	v_mul_f32_e32 v21, v21, v155
	v_mul_f32_e32 v22, v22, v155
	v_mul_f32_e32 v23, v23, v155
	v_mul_f32_e32 v24, v24, v155
	v_mul_f32_e32 v25, v25, v155
	v_mul_f32_e32 v26, v26, v155
	v_mul_f32_e32 v27, v27, v155
	v_mul_f32_e32 v28, v28, v155
	v_mul_f32_e32 v29, v29, v155
	v_mul_f32_e32 v30, v30, v155
	v_mul_f32_e32 v31, v31, v155
	v_cvt_pk_bf16_f32 v144, v16, v17
	v_cvt_pk_bf16_f32 v145, v18, v19
	v_cvt_pk_bf16_f32 v148, v20, v21
	v_cvt_pk_bf16_f32 v149, v22, v23
	v_cvt_pk_bf16_f32 v146, v24, v25
	v_cvt_pk_bf16_f32 v147, v26, v27
	v_cvt_pk_bf16_f32 v150, v28, v29
	v_cvt_pk_bf16_f32 v151, v30, v31
	s_nop 1
	v_permlane32_swap_b32_e32 v144, v146
	v_permlane32_swap_b32_e32 v145, v147
	v_permlane32_swap_b32_e32 v148, v150
	v_permlane32_swap_b32_e32 v149, v151
	global_store_dwordx4 v158, v[144:147], s[12:13]
	global_store_dwordx4 v158, v[148:151], s[12:13] offset:16
	s_branch .Lkv_done

.Lq_loop:
	s_waitcnt vmcnt(6)
	ds_write_b128 v245, v[228:231] offset:16896
	ds_write_b128 v245, v[238:241] offset:25344
	s_add_u32 s0, s5, -1
	s_min_u32 s0, s25, s0
	s_mul_hi_u32 s1, s0, 0x38e38e39
	s_lshr_b32 s1, s1, 2
	s_mul_i32 s1, s1, 18
	s_sub_u32 s0, s0, s1
	s_lshl_b32 s0, s0, 14
	s_add_u32 s10, s8, s0
	s_addc_u32 s11, s9, 0
	global_load_dwordx4 v[228:231], v246, s[10:11]
	global_load_dwordx4 v[238:241], v164, s[10:11]
	s_add_u32 s25, s25, 1
	s_mul_hi_u32 s1, s4, 0x38e38e39
	s_lshr_b32 s1, s1, 2
	s_mul_i32 s1, s1, 18
	s_sub_u32 s0, s4, s1
	s_mul_hi_u32 s1, s0, 0xaaaaaaab
	s_lshr_b32 s1, s1, 1
	s_mul_i32 s32, s1, 3
	s_sub_u32 s32, s0, s32
	s_mul_i32 s1, s1, 4352
	s_add_u32 s1, s1, s18
	s_mul_i32 s1, s1, 192
	s_lshl_b32 s54, s32, 6
	s_add_u32 s1, s1, s54
	s_add_u32 s1, s1, 0x108dd000
	s_add_u32 s14, s50, s1
	s_addc_u32 s15, s51, 0
	s_cmp_eq_u32 s32, 2
	s_cselect_b32 s17, s19, 0
	s_add_u32 s17, s17, 1
	ds_read_b128 v[188:191], v247 offset:0
	ds_read_b128 v[192:195], v247 offset:32
	ds_read_b128 v[196:199], v247 offset:64
	ds_read_b128 v[200:203], v247 offset:96
	ds_read_b128 v[204:207], v247 offset:128
	ds_read_b128 v[208:211], v247 offset:160
	ds_read_b128 v[212:215], v247 offset:192
	ds_read_b128 v[216:219], v247 offset:224
	s_cmp_eq_u32 s16, 1
	s_cbranch_scc1 .Lq_ep0
	s_cmp_eq_u32 s16, 2
	s_cbranch_scc1 .Lq_er0
	s_waitcnt lgkmcnt(7)
	v_mfma_f32_32x32x16_bf16 v[0:15], v[188:191], v[48:51], 0
	ds_read_b128 v[188:191], v247 offset:256
	global_load_dword v156, v243, s[26:27]
	s_waitcnt lgkmcnt(7)
	v_mfma_f32_32x32x16_bf16 v[0:15], v[192:195], v[52:55], v[0:15]
	ds_read_b128 v[192:195], v247 offset:288
	global_load_dword v157, v243, s[26:27]
	s_waitcnt lgkmcnt(7)
	v_mfma_f32_32x32x16_bf16 v[0:15], v[196:199], v[56:59], v[0:15]
	ds_read_b128 v[196:199], v247 offset:320
	s_waitcnt lgkmcnt(7)
	v_mfma_f32_32x32x16_bf16 v[0:15], v[200:203], v[60:63], v[0:15]
	ds_read_b128 v[200:203], v247 offset:352
	s_waitcnt lgkmcnt(7)
	v_mfma_f32_32x32x16_bf16 v[0:15], v[204:207], v[64:67], v[0:15]
	ds_read_b128 v[204:207], v247 offset:384
	s_waitcnt lgkmcnt(7)
	v_mfma_f32_32x32x16_bf16 v[0:15], v[208:211], v[68:71], v[0:15]
	ds_read_b128 v[208:211], v247 offset:416
	s_waitcnt lgkmcnt(7)
	v_mfma_f32_32x32x16_bf16 v[0:15], v[212:215], v[72:75], v[0:15]
	ds_read_b128 v[212:215], v247 offset:448
	s_waitcnt lgkmcnt(7)
	v_mfma_f32_32x32x16_bf16 v[0:15], v[216:219], v[76:79], v[0:15]
	ds_read_b128 v[216:219], v247 offset:480
	s_waitcnt lgkmcnt(7)
	v_mfma_f32_32x32x16_bf16 v[0:15], v[188:191], v[96:99], v[0:15]
	s_waitcnt lgkmcnt(6)
	v_mfma_f32_32x32x16_bf16 v[0:15], v[192:195], v[100:103], v[0:15]
	s_waitcnt lgkmcnt(5)
	v_mfma_f32_32x32x16_bf16 v[0:15], v[196:199], v[104:107], v[0:15]
	s_waitcnt lgkmcnt(4)
	v_mfma_f32_32x32x16_bf16 v[0:15], v[200:203], v[108:111], v[0:15]
	s_waitcnt lgkmcnt(3)
	v_mfma_f32_32x32x16_bf16 v[0:15], v[204:207], v[112:115], v[0:15]
	s_waitcnt lgkmcnt(2)
	v_mfma_f32_32x32x16_bf16 v[0:15], v[208:211], v[116:119], v[0:15]
	s_waitcnt lgkmcnt(1)
	v_mfma_f32_32x32x16_bf16 v[0:15], v[212:215], v[120:123], v[0:15]
	s_waitcnt lgkmcnt(0)
	v_mfma_f32_32x32x16_bf16 v[0:15], v[216:219], v[124:127], v[0:15]
	s_branch .Lq_ex0
.Lq_ep0:
	s_waitcnt lgkmcnt(7)
	v_mfma_f32_32x32x16_bf16 v[0:15], v[188:191], v[48:51], 0
	ds_read_b128 v[188:191], v247 offset:256
	v_mul_f32_e32 v16, v16, v155
	v_mul_f32_e32 v17, v17, v155
	v_mul_f32_e32 v18, v18, v155
	v_mul_f32_e32 v19, v19, v155
	s_waitcnt lgkmcnt(7)
	v_mfma_f32_32x32x16_bf16 v[0:15], v[192:195], v[52:55], v[0:15]
	ds_read_b128 v[192:195], v247 offset:288
	v_mul_f32_e32 v20, v20, v155
	v_mul_f32_e32 v21, v21, v155
	v_mul_f32_e32 v22, v22, v155
	v_mul_f32_e32 v23, v23, v155
	s_waitcnt lgkmcnt(7)
	v_mfma_f32_32x32x16_bf16 v[0:15], v[196:199], v[56:59], v[0:15]
	ds_read_b128 v[196:199], v247 offset:320
	v_mul_f32_e32 v24, v24, v155
	v_mul_f32_e32 v25, v25, v155
	v_mul_f32_e32 v26, v26, v155
	v_mul_f32_e32 v27, v27, v155
	s_waitcnt lgkmcnt(7)
	v_mfma_f32_32x32x16_bf16 v[0:15], v[200:203], v[60:63], v[0:15]
	ds_read_b128 v[200:203], v247 offset:352
	v_mul_f32_e32 v28, v28, v155
	v_mul_f32_e32 v29, v29, v155
	v_mul_f32_e32 v30, v30, v155
	v_mul_f32_e32 v31, v31, v155
	s_waitcnt lgkmcnt(7)
	v_mfma_f32_32x32x16_bf16 v[0:15], v[204:207], v[64:67], v[0:15]
	ds_read_b128 v[204:207], v247 offset:384
	v_mul_f32_e32 v16, s23, v16
	v_mul_f32_e32 v17, s23, v17
	v_mul_f32_e32 v18, s23, v18
	v_mul_f32_e32 v19, s23, v19
	s_waitcnt lgkmcnt(7)
	v_mfma_f32_32x32x16_bf16 v[0:15], v[208:211], v[68:71], v[0:15]
	ds_read_b128 v[208:211], v247 offset:416
	v_mul_f32_e32 v20, s23, v20
	v_mul_f32_e32 v21, s23, v21
	v_mul_f32_e32 v22, s23, v22
	v_mul_f32_e32 v23, s23, v23
	s_waitcnt lgkmcnt(7)
	v_mfma_f32_32x32x16_bf16 v[0:15], v[212:215], v[72:75], v[0:15]
	ds_read_b128 v[212:215], v247 offset:448
	v_mul_f32_e32 v24, s23, v24
	v_mul_f32_e32 v25, s23, v25
	v_mul_f32_e32 v26, s23, v26
	v_mul_f32_e32 v27, s23, v27
	s_waitcnt lgkmcnt(7)
	v_mfma_f32_32x32x16_bf16 v[0:15], v[216:219], v[76:79], v[0:15]
	ds_read_b128 v[216:219], v247 offset:480
	v_mul_f32_e32 v28, s23, v28
	v_mul_f32_e32 v29, s23, v29
	v_mul_f32_e32 v30, s23, v30
	v_mul_f32_e32 v31, s23, v31
	s_waitcnt lgkmcnt(7)
	v_mfma_f32_32x32x16_bf16 v[0:15], v[188:191], v[96:99], v[0:15]
	v_cvt_pk_bf16_f32 v144, v16, v17
	v_cvt_pk_bf16_f32 v145, v18, v19
	v_cvt_pk_bf16_f32 v148, v20, v21
	v_cvt_pk_bf16_f32 v149, v22, v23
	s_waitcnt lgkmcnt(6)
	v_mfma_f32_32x32x16_bf16 v[0:15], v[192:195], v[100:103], v[0:15]
	v_cvt_pk_bf16_f32 v146, v24, v25
	v_cvt_pk_bf16_f32 v147, v26, v27
	v_cvt_pk_bf16_f32 v150, v28, v29
	v_cvt_pk_bf16_f32 v151, v30, v31
	s_waitcnt lgkmcnt(5)
	v_mfma_f32_32x32x16_bf16 v[0:15], v[196:199], v[104:107], v[0:15]
	s_nop 1
	v_permlane32_swap_b32_e32 v144, v146
	v_permlane32_swap_b32_e32 v145, v147
	v_permlane32_swap_b32_e32 v148, v150
	s_waitcnt lgkmcnt(4)
	v_mfma_f32_32x32x16_bf16 v[0:15], v[200:203], v[108:111], v[0:15]
	v_permlane32_swap_b32_e32 v149, v151
	global_store_dwordx4 v244, v[144:147], s[12:13]
	global_store_dwordx4 v244, v[148:151], s[12:13] offset:16
	s_waitcnt lgkmcnt(3)
	v_mfma_f32_32x32x16_bf16 v[0:15], v[204:207], v[112:115], v[0:15]
	s_waitcnt lgkmcnt(2)
	v_mfma_f32_32x32x16_bf16 v[0:15], v[208:211], v[116:119], v[0:15]
	s_waitcnt lgkmcnt(1)
	v_mfma_f32_32x32x16_bf16 v[0:15], v[212:215], v[120:123], v[0:15]
	s_waitcnt lgkmcnt(0)
	v_mfma_f32_32x32x16_bf16 v[0:15], v[216:219], v[124:127], v[0:15]
	s_branch .Lq_ex0
.Lq_er0:
	s_waitcnt lgkmcnt(7)
	v_mfma_f32_32x32x16_bf16 v[0:15], v[188:191], v[48:51], 0
	ds_read_b128 v[188:191], v247 offset:256
	v_mul_f32_e32 v16, v16, v155
	v_mul_f32_e32 v17, v17, v155
	v_mul_f32_e32 v18, v18, v155
	v_mul_f32_e32 v19, v19, v155
	v_mul_f32_e32 v20, v20, v155
	v_mul_f32_e32 v21, v21, v155
	s_waitcnt lgkmcnt(7)
	v_mfma_f32_32x32x16_bf16 v[0:15], v[192:195], v[52:55], v[0:15]
	ds_read_b128 v[192:195], v247 offset:288
	v_mul_f32_e32 v22, v22, v155
	v_mul_f32_e32 v23, v23, v155
	v_mul_f32_e32 v24, v24, v155
	v_mul_f32_e32 v25, v25, v155
	v_mul_f32_e32 v26, v26, v155
	v_mul_f32_e32 v27, v27, v155
	s_waitcnt lgkmcnt(7)
	v_mfma_f32_32x32x16_bf16 v[0:15], v[196:199], v[56:59], v[0:15]
	ds_read_b128 v[196:199], v247 offset:320
	v_mul_f32_e32 v28, v28, v155
	v_mul_f32_e32 v29, v29, v155
	v_mul_f32_e32 v30, v30, v155
	v_mul_f32_e32 v31, v31, v155
	v_mul_f32_e32 v162, v20, v134
	v_mul_f32_e32 v163, v16, v134
	s_waitcnt lgkmcnt(7)
	v_mfma_f32_32x32x16_bf16 v[0:15], v[200:203], v[60:63], v[0:15]
	ds_read_b128 v[200:203], v247 offset:352
	v_fma_f32 v16, v16, v130, -v162
	v_fma_f32 v20, v20, v130, v163
	v_mul_f32_e32 v162, v21, v135
	v_mul_f32_e32 v163, v17, v135
	v_fma_f32 v17, v17, v131, -v162
	v_fma_f32 v21, v21, v131, v163
	s_waitcnt lgkmcnt(7)
	v_mfma_f32_32x32x16_bf16 v[0:15], v[204:207], v[64:67], v[0:15]
	ds_read_b128 v[204:207], v247 offset:384
	v_mul_f32_e32 v162, v22, v136
	v_mul_f32_e32 v163, v18, v136
	v_fma_f32 v18, v18, v132, -v162
	v_fma_f32 v22, v22, v132, v163
	v_mul_f32_e32 v162, v23, v137
	v_mul_f32_e32 v163, v19, v137
	s_waitcnt lgkmcnt(7)
	v_mfma_f32_32x32x16_bf16 v[0:15], v[208:211], v[68:71], v[0:15]
	ds_read_b128 v[208:211], v247 offset:416
	v_fma_f32 v19, v19, v133, -v162
	v_fma_f32 v23, v23, v133, v163
	v_mul_f32_e32 v162, v28, v158
	v_mul_f32_e32 v163, v24, v158
	v_fma_f32 v24, v24, v138, -v162
	v_fma_f32 v28, v28, v138, v163
	s_waitcnt lgkmcnt(7)
	v_mfma_f32_32x32x16_bf16 v[0:15], v[212:215], v[72:75], v[0:15]
	ds_read_b128 v[212:215], v247 offset:448
	v_mul_f32_e32 v162, v29, v159
	v_mul_f32_e32 v163, v25, v159
	v_fma_f32 v25, v25, v139, -v162
	v_fma_f32 v29, v29, v139, v163
	v_mul_f32_e32 v162, v30, v160
	v_mul_f32_e32 v163, v26, v160
	s_waitcnt lgkmcnt(7)
	v_mfma_f32_32x32x16_bf16 v[0:15], v[216:219], v[76:79], v[0:15]
	ds_read_b128 v[216:219], v247 offset:480
	v_fma_f32 v26, v26, v140, -v162
	v_fma_f32 v30, v30, v140, v163
	v_mul_f32_e32 v162, v31, v161
	v_mul_f32_e32 v163, v27, v161
	v_fma_f32 v27, v27, v141, -v162
	v_fma_f32 v31, v31, v141, v163
	s_waitcnt lgkmcnt(7)
	v_mfma_f32_32x32x16_bf16 v[0:15], v[188:191], v[96:99], v[0:15]
	v_mul_f32_e32 v16, s23, v16
	v_mul_f32_e32 v17, s23, v17
	v_mul_f32_e32 v18, s23, v18
	v_mul_f32_e32 v19, s23, v19
	v_mul_f32_e32 v20, s23, v20
	v_mul_f32_e32 v21, s23, v21
	s_waitcnt lgkmcnt(6)
	v_mfma_f32_32x32x16_bf16 v[0:15], v[192:195], v[100:103], v[0:15]
	v_mul_f32_e32 v22, s23, v22
	v_mul_f32_e32 v23, s23, v23
	v_mul_f32_e32 v24, s23, v24
	v_mul_f32_e32 v25, s23, v25
	v_mul_f32_e32 v26, s23, v26
	v_mul_f32_e32 v27, s23, v27
	s_waitcnt lgkmcnt(5)
	v_mfma_f32_32x32x16_bf16 v[0:15], v[196:199], v[104:107], v[0:15]
	v_mul_f32_e32 v28, s23, v28
	v_mul_f32_e32 v29, s23, v29
	v_mul_f32_e32 v30, s23, v30
	v_mul_f32_e32 v31, s23, v31
	v_cvt_pk_bf16_f32 v144, v16, v17
	v_cvt_pk_bf16_f32 v145, v18, v19
	s_waitcnt lgkmcnt(4)
	v_mfma_f32_32x32x16_bf16 v[0:15], v[200:203], v[108:111], v[0:15]
	v_cvt_pk_bf16_f32 v148, v20, v21
	v_cvt_pk_bf16_f32 v149, v22, v23
	v_cvt_pk_bf16_f32 v146, v24, v25
	v_cvt_pk_bf16_f32 v147, v26, v27
	v_cvt_pk_bf16_f32 v150, v28, v29
	v_cvt_pk_bf16_f32 v151, v30, v31
	s_waitcnt lgkmcnt(3)
	v_mfma_f32_32x32x16_bf16 v[0:15], v[204:207], v[112:115], v[0:15]
	s_nop 1
	v_permlane32_swap_b32_e32 v144, v146
	v_permlane32_swap_b32_e32 v145, v147
	v_permlane32_swap_b32_e32 v148, v150
	v_permlane32_swap_b32_e32 v149, v151
	global_store_dwordx4 v244, v[144:147], s[12:13]
	s_waitcnt lgkmcnt(2)
	v_mfma_f32_32x32x16_bf16 v[0:15], v[208:211], v[116:119], v[0:15]
	global_store_dwordx4 v244, v[148:151], s[12:13] offset:16
	s_waitcnt lgkmcnt(1)
	v_mfma_f32_32x32x16_bf16 v[0:15], v[212:215], v[120:123], v[0:15]
	s_waitcnt lgkmcnt(0)
	v_mfma_f32_32x32x16_bf16 v[0:15], v[216:219], v[124:127], v[0:15]
.Lq_ex0:
	v_mov_b32_e32 v155, v154
	s_mov_b64 s[12:13], s[14:15]
	s_mov_b32 s16, s17
	s_add_u32 s4, s4, 1
	s_waitcnt lgkmcnt(0)
	s_barrier
	s_cmp_ge_u32 s4, s5
	s_cbranch_scc1 .Lq_drain0
	s_cmp_lg_u32 s4, s6
	s_cbranch_scc1 .Lq_ns0
	s_nop 7
	s_nop 7
	s_cmp_eq_u32 s16, 2
	s_cbranch_scc1 .Lq_sr0
	v_mul_f32_e32 v0, v0, v155
	v_mul_f32_e32 v1, v1, v155
	v_mul_f32_e32 v2, v2, v155
	v_mul_f32_e32 v3, v3, v155
	v_mul_f32_e32 v4, v4, v155
	v_mul_f32_e32 v5, v5, v155
	v_mul_f32_e32 v6, v6, v155
	v_mul_f32_e32 v7, v7, v155
	v_mul_f32_e32 v8, v8, v155
	v_mul_f32_e32 v9, v9, v155
	v_mul_f32_e32 v10, v10, v155
	v_mul_f32_e32 v11, v11, v155
	v_mul_f32_e32 v12, v12, v155
	v_mul_f32_e32 v13, v13, v155
	v_mul_f32_e32 v14, v14, v155
	v_mul_f32_e32 v15, v15, v155
	v_mul_f32_e32 v0, s23, v0
	v_mul_f32_e32 v1, s23, v1
	v_mul_f32_e32 v2, s23, v2
	v_mul_f32_e32 v3, s23, v3
	v_mul_f32_e32 v4, s23, v4
	v_mul_f32_e32 v5, s23, v5
	v_mul_f32_e32 v6, s23, v6
	v_mul_f32_e32 v7, s23, v7
	v_mul_f32_e32 v8, s23, v8
	v_mul_f32_e32 v9, s23, v9
	v_mul_f32_e32 v10, s23, v10
	v_mul_f32_e32 v11, s23, v11
	v_mul_f32_e32 v12, s23, v12
	v_mul_f32_e32 v13, s23, v13
	v_mul_f32_e32 v14, s23, v14
	v_mul_f32_e32 v15, s23, v15
	v_cvt_pk_bf16_f32 v144, v0, v1
	v_cvt_pk_bf16_f32 v145, v2, v3
	v_cvt_pk_bf16_f32 v148, v4, v5
	v_cvt_pk_bf16_f32 v149, v6, v7
	v_cvt_pk_bf16_f32 v146, v8, v9
	v_cvt_pk_bf16_f32 v147, v10, v11
	v_cvt_pk_bf16_f32 v150, v12, v13
	v_cvt_pk_bf16_f32 v151, v14, v15
	s_nop 1
	v_permlane32_swap_b32_e32 v144, v146
	v_permlane32_swap_b32_e32 v145, v147
	v_permlane32_swap_b32_e32 v148, v150
	v_permlane32_swap_b32_e32 v149, v151
	global_store_dwordx4 v244, v[144:147], s[12:13]
	global_store_dwordx4 v244, v[148:151], s[12:13] offset:16
	s_branch .Lq_sx0
.Lq_sr0:
	v_mul_f32_e32 v0, v0, v155
	v_mul_f32_e32 v1, v1, v155
	v_mul_f32_e32 v2, v2, v155
	v_mul_f32_e32 v3, v3, v155
	v_mul_f32_e32 v4, v4, v155
	v_mul_f32_e32 v5, v5, v155
	v_mul_f32_e32 v6, v6, v155
	v_mul_f32_e32 v7, v7, v155
	v_mul_f32_e32 v8, v8, v155
	v_mul_f32_e32 v9, v9, v155
	v_mul_f32_e32 v10, v10, v155
	v_mul_f32_e32 v11, v11, v155
	v_mul_f32_e32 v12, v12, v155
	v_mul_f32_e32 v13, v13, v155
	v_mul_f32_e32 v14, v14, v155
	v_mul_f32_e32 v15, v15, v155
	v_mul_f32_e32 v162, v4, v134
	v_mul_f32_e32 v163, v0, v134
	v_fma_f32 v0, v0, v130, -v162
	v_fma_f32 v4, v4, v130, v163
	v_mul_f32_e32 v162, v5, v135
	v_mul_f32_e32 v163, v1, v135
	v_fma_f32 v1, v1, v131, -v162
	v_fma_f32 v5, v5, v131, v163
	v_mul_f32_e32 v162, v6, v136
	v_mul_f32_e32 v163, v2, v136
	v_fma_f32 v2, v2, v132, -v162
	v_fma_f32 v6, v6, v132, v163
	v_mul_f32_e32 v162, v7, v137
	v_mul_f32_e32 v163, v3, v137
	v_fma_f32 v3, v3, v133, -v162
	v_fma_f32 v7, v7, v133, v163
	v_mul_f32_e32 v162, v12, v158
	v_mul_f32_e32 v163, v8, v158
	v_fma_f32 v8, v8, v138, -v162
	v_fma_f32 v12, v12, v138, v163
	v_mul_f32_e32 v162, v13, v159
	v_mul_f32_e32 v163, v9, v159
	v_fma_f32 v9, v9, v139, -v162
	v_fma_f32 v13, v13, v139, v163
	v_mul_f32_e32 v162, v14, v160
	v_mul_f32_e32 v163, v10, v160
	v_fma_f32 v10, v10, v140, -v162
	v_fma_f32 v14, v14, v140, v163
	v_mul_f32_e32 v162, v15, v161
	v_mul_f32_e32 v163, v11, v161
	v_fma_f32 v11, v11, v141, -v162
	v_fma_f32 v15, v15, v141, v163
	v_mul_f32_e32 v0, s23, v0
	v_mul_f32_e32 v1, s23, v1
	v_mul_f32_e32 v2, s23, v2
	v_mul_f32_e32 v3, s23, v3
	v_mul_f32_e32 v4, s23, v4
	v_mul_f32_e32 v5, s23, v5
	v_mul_f32_e32 v6, s23, v6
	v_mul_f32_e32 v7, s23, v7
	v_mul_f32_e32 v8, s23, v8
	v_mul_f32_e32 v9, s23, v9
	v_mul_f32_e32 v10, s23, v10
	v_mul_f32_e32 v11, s23, v11
	v_mul_f32_e32 v12, s23, v12
	v_mul_f32_e32 v13, s23, v13
	v_mul_f32_e32 v14, s23, v14
	v_mul_f32_e32 v15, s23, v15
	v_cvt_pk_bf16_f32 v144, v0, v1
	v_cvt_pk_bf16_f32 v145, v2, v3
	v_cvt_pk_bf16_f32 v148, v4, v5
	v_cvt_pk_bf16_f32 v149, v6, v7
	v_cvt_pk_bf16_f32 v146, v8, v9
	v_cvt_pk_bf16_f32 v147, v10, v11
	v_cvt_pk_bf16_f32 v150, v12, v13
	v_cvt_pk_bf16_f32 v151, v14, v15
	s_nop 1
	v_permlane32_swap_b32_e32 v144, v146
	v_permlane32_swap_b32_e32 v145, v147
	v_permlane32_swap_b32_e32 v148, v150
	v_permlane32_swap_b32_e32 v149, v151
	global_store_dwordx4 v244, v[144:147], s[12:13]
	global_store_dwordx4 v244, v[148:151], s[12:13] offset:16
.Lq_sx0:
	s_mov_b32 s16, 0
	s_mul_hi_u32 s59, s4, 0x38e38e39
	s_lshr_b32 s59, s59, 2
	s_mov_b32 s6, s5
	s_lshl_b32 s32, s59, 8
	s_lshr_b32 s54, s32, 12
	s_and_b32 s55, s32, 0xfff
	s_sub_u32 s56, s32, 0x8000
	s_lshr_b32 s56, s56, 8
	s_movk_i32 s58, 0x1000
	s_cmp_lt_u32 s32, 0x8000
	s_cselect_b32 s54, s54, s56
	s_cselect_b32 s55, s55, s58
	s_cselect_b32 s19, 1, 0
	s_mul_i32 s54, s54, 26112
	s_add_u32 s18, s54, s55
	s_mul_i32 s54, s32, 5184
	s_add_u32 s54, s54, 0x5cbd000
	s_add_u32 s20, s50, s54
	s_addc_u32 s21, s51, 0
	s_lshl_b32 s54, s32, 3
	s_add_u32 s54, s54, 0x1079000
	s_add_u32 s26, s50, s54
	s_addc_u32 s27, s51, 0
	global_load_dwordx4 v[48:51], v242, s[20:21] offset:0
	global_load_dwordx4 v[52:55], v242, s[20:21] offset:32
	global_load_dwordx4 v[56:59], v242, s[20:21] offset:64
	global_load_dwordx4 v[60:63], v242, s[20:21] offset:96
	global_load_dwordx4 v[64:67], v242, s[20:21] offset:128
	global_load_dwordx4 v[68:71], v242, s[20:21] offset:160
	global_load_dwordx4 v[72:75], v242, s[20:21] offset:192
	global_load_dwordx4 v[76:79], v242, s[20:21] offset:224
	global_load_dwordx4 v[96:99], v242, s[20:21] offset:256
	global_load_dwordx4 v[100:103], v242, s[20:21] offset:288
	global_load_dwordx4 v[104:107], v242, s[20:21] offset:320
	global_load_dwordx4 v[108:111], v242, s[20:21] offset:352
	global_load_dwordx4 v[112:115], v242, s[20:21] offset:384
	global_load_dwordx4 v[116:119], v242, s[20:21] offset:416
	global_load_dwordx4 v[120:123], v242, s[20:21] offset:448
	global_load_dwordx4 v[124:127], v242, s[20:21] offset:480
	global_load_dword v154, v243, s[26:27]
	v_add_u32_e32 v162, s55, v250
	v_and_b32_e32 v162, 0xfff, v162
	v_lshrrev_b32_e32 v163, 6, v162
	v_lshl_add_u32 v163, v163, 5, v251
	global_load_dwordx4 v[130:133], v163, s[30:31]
	global_load_dwordx4 v[134:137], v163, s[30:31] offset:2048
	v_and_b32_e32 v162, 63, v162
	v_lshl_add_u32 v162, v162, 5, v251
	global_load_dwordx4 v[138:141], v162, s[30:31]
	global_load_dwordx4 v[158:161], v162, s[30:31] offset:2048
	s_waitcnt vmcnt(0)
.Lq_ns0:
	s_waitcnt vmcnt(6)
	ds_write_b128 v245, v[220:223] offset:0
	ds_write_b128 v245, v[224:227] offset:8448
	s_add_u32 s0, s5, -1
	s_min_u32 s0, s25, s0
	s_mul_hi_u32 s1, s0, 0x38e38e39
	s_lshr_b32 s1, s1, 2
	s_mul_i32 s1, s1, 18
	s_sub_u32 s0, s0, s1
	s_lshl_b32 s0, s0, 14
	s_add_u32 s10, s8, s0
	s_addc_u32 s11, s9, 0
	global_load_dwordx4 v[220:223], v246, s[10:11]
	global_load_dwordx4 v[224:227], v164, s[10:11]
	s_add_u32 s25, s25, 1
	s_mul_hi_u32 s1, s4, 0x38e38e39
	s_lshr_b32 s1, s1, 2
	s_mul_i32 s1, s1, 18
	s_sub_u32 s0, s4, s1
	s_mul_hi_u32 s1, s0, 0xaaaaaaab
	s_lshr_b32 s1, s1, 1
	s_mul_i32 s32, s1, 3
	s_sub_u32 s32, s0, s32
	s_mul_i32 s1, s1, 4352
	s_add_u32 s1, s1, s18
	s_mul_i32 s1, s1, 192
	s_lshl_b32 s54, s32, 6
	s_add_u32 s1, s1, s54
	s_add_u32 s1, s1, 0x108dd000
	s_add_u32 s14, s50, s1
	s_addc_u32 s15, s51, 0
	s_cmp_eq_u32 s32, 2
	s_cselect_b32 s17, s19, 0
	s_add_u32 s17, s17, 1
	ds_read_b128 v[188:191], v247 offset:16896
	ds_read_b128 v[192:195], v247 offset:16928
	ds_read_b128 v[196:199], v247 offset:16960
	ds_read_b128 v[200:203], v247 offset:16992
	ds_read_b128 v[204:207], v247 offset:17024
	ds_read_b128 v[208:211], v247 offset:17056
	ds_read_b128 v[212:215], v247 offset:17088
	ds_read_b128 v[216:219], v247 offset:17120
	s_cmp_eq_u32 s16, 1
	s_cbranch_scc1 .Lq_ep1
	s_cmp_eq_u32 s16, 2
	s_cbranch_scc1 .Lq_er1
	s_waitcnt lgkmcnt(7)
	v_mfma_f32_32x32x16_bf16 v[16:31], v[188:191], v[48:51], 0
	ds_read_b128 v[188:191], v247 offset:17152
	global_load_dword v156, v243, s[26:27]
	s_waitcnt lgkmcnt(7)
	v_mfma_f32_32x32x16_bf16 v[16:31], v[192:195], v[52:55], v[16:31]
	ds_read_b128 v[192:195], v247 offset:17184
	global_load_dword v157, v243, s[26:27]
	s_waitcnt lgkmcnt(7)
	v_mfma_f32_32x32x16_bf16 v[16:31], v[196:199], v[56:59], v[16:31]
	ds_read_b128 v[196:199], v247 offset:17216
	s_waitcnt lgkmcnt(7)
	v_mfma_f32_32x32x16_bf16 v[16:31], v[200:203], v[60:63], v[16:31]
	ds_read_b128 v[200:203], v247 offset:17248
	s_waitcnt lgkmcnt(7)
	v_mfma_f32_32x32x16_bf16 v[16:31], v[204:207], v[64:67], v[16:31]
	ds_read_b128 v[204:207], v247 offset:17280
	s_waitcnt lgkmcnt(7)
	v_mfma_f32_32x32x16_bf16 v[16:31], v[208:211], v[68:71], v[16:31]
	ds_read_b128 v[208:211], v247 offset:17312
	s_waitcnt lgkmcnt(7)
	v_mfma_f32_32x32x16_bf16 v[16:31], v[212:215], v[72:75], v[16:31]
	ds_read_b128 v[212:215], v247 offset:17344
	s_waitcnt lgkmcnt(7)
	v_mfma_f32_32x32x16_bf16 v[16:31], v[216:219], v[76:79], v[16:31]
	ds_read_b128 v[216:219], v247 offset:17376
	s_waitcnt lgkmcnt(7)
	v_mfma_f32_32x32x16_bf16 v[16:31], v[188:191], v[96:99], v[16:31]
	s_waitcnt lgkmcnt(6)
	v_mfma_f32_32x32x16_bf16 v[16:31], v[192:195], v[100:103], v[16:31]
	s_waitcnt lgkmcnt(5)
	v_mfma_f32_32x32x16_bf16 v[16:31], v[196:199], v[104:107], v[16:31]
	s_waitcnt lgkmcnt(4)
	v_mfma_f32_32x32x16_bf16 v[16:31], v[200:203], v[108:111], v[16:31]
	s_waitcnt lgkmcnt(3)
	v_mfma_f32_32x32x16_bf16 v[16:31], v[204:207], v[112:115], v[16:31]
	s_waitcnt lgkmcnt(2)
	v_mfma_f32_32x32x16_bf16 v[16:31], v[208:211], v[116:119], v[16:31]
	s_waitcnt lgkmcnt(1)
	v_mfma_f32_32x32x16_bf16 v[16:31], v[212:215], v[120:123], v[16:31]
	s_waitcnt lgkmcnt(0)
	v_mfma_f32_32x32x16_bf16 v[16:31], v[216:219], v[124:127], v[16:31]
	s_branch .Lq_ex1
.Lq_ep1:
	s_waitcnt lgkmcnt(7)
	v_mfma_f32_32x32x16_bf16 v[16:31], v[188:191], v[48:51], 0
	ds_read_b128 v[188:191], v247 offset:17152
	v_mul_f32_e32 v0, v0, v155
	v_mul_f32_e32 v1, v1, v155
	v_mul_f32_e32 v2, v2, v155
	v_mul_f32_e32 v3, v3, v155
	s_waitcnt lgkmcnt(7)
	v_mfma_f32_32x32x16_bf16 v[16:31], v[192:195], v[52:55], v[16:31]
	ds_read_b128 v[192:195], v247 offset:17184
	v_mul_f32_e32 v4, v4, v155
	v_mul_f32_e32 v5, v5, v155
	v_mul_f32_e32 v6, v6, v155
	v_mul_f32_e32 v7, v7, v155
	s_waitcnt lgkmcnt(7)
	v_mfma_f32_32x32x16_bf16 v[16:31], v[196:199], v[56:59], v[16:31]
	ds_read_b128 v[196:199], v247 offset:17216
	v_mul_f32_e32 v8, v8, v155
	v_mul_f32_e32 v9, v9, v155
	v_mul_f32_e32 v10, v10, v155
	v_mul_f32_e32 v11, v11, v155
	s_waitcnt lgkmcnt(7)
	v_mfma_f32_32x32x16_bf16 v[16:31], v[200:203], v[60:63], v[16:31]
	ds_read_b128 v[200:203], v247 offset:17248
	v_mul_f32_e32 v12, v12, v155
	v_mul_f32_e32 v13, v13, v155
	v_mul_f32_e32 v14, v14, v155
	v_mul_f32_e32 v15, v15, v155
	s_waitcnt lgkmcnt(7)
	v_mfma_f32_32x32x16_bf16 v[16:31], v[204:207], v[64:67], v[16:31]
	ds_read_b128 v[204:207], v247 offset:17280
	v_mul_f32_e32 v0, s23, v0
	v_mul_f32_e32 v1, s23, v1
	v_mul_f32_e32 v2, s23, v2
	v_mul_f32_e32 v3, s23, v3
	s_waitcnt lgkmcnt(7)
	v_mfma_f32_32x32x16_bf16 v[16:31], v[208:211], v[68:71], v[16:31]
	ds_read_b128 v[208:211], v247 offset:17312
	v_mul_f32_e32 v4, s23, v4
	v_mul_f32_e32 v5, s23, v5
	v_mul_f32_e32 v6, s23, v6
	v_mul_f32_e32 v7, s23, v7
	s_waitcnt lgkmcnt(7)
	v_mfma_f32_32x32x16_bf16 v[16:31], v[212:215], v[72:75], v[16:31]
	ds_read_b128 v[212:215], v247 offset:17344
	v_mul_f32_e32 v8, s23, v8
	v_mul_f32_e32 v9, s23, v9
	v_mul_f32_e32 v10, s23, v10
	v_mul_f32_e32 v11, s23, v11
	s_waitcnt lgkmcnt(7)
	v_mfma_f32_32x32x16_bf16 v[16:31], v[216:219], v[76:79], v[16:31]
	ds_read_b128 v[216:219], v247 offset:17376
	v_mul_f32_e32 v12, s23, v12
	v_mul_f32_e32 v13, s23, v13
	v_mul_f32_e32 v14, s23, v14
	v_mul_f32_e32 v15, s23, v15
	s_waitcnt lgkmcnt(7)
	v_mfma_f32_32x32x16_bf16 v[16:31], v[188:191], v[96:99], v[16:31]
	v_cvt_pk_bf16_f32 v144, v0, v1
	v_cvt_pk_bf16_f32 v145, v2, v3
	v_cvt_pk_bf16_f32 v148, v4, v5
	v_cvt_pk_bf16_f32 v149, v6, v7
	s_waitcnt lgkmcnt(6)
	v_mfma_f32_32x32x16_bf16 v[16:31], v[192:195], v[100:103], v[16:31]
	v_cvt_pk_bf16_f32 v146, v8, v9
	v_cvt_pk_bf16_f32 v147, v10, v11
	v_cvt_pk_bf16_f32 v150, v12, v13
	v_cvt_pk_bf16_f32 v151, v14, v15
	s_waitcnt lgkmcnt(5)
	v_mfma_f32_32x32x16_bf16 v[16:31], v[196:199], v[104:107], v[16:31]
	s_nop 1
	v_permlane32_swap_b32_e32 v144, v146
	v_permlane32_swap_b32_e32 v145, v147
	v_permlane32_swap_b32_e32 v148, v150
	s_waitcnt lgkmcnt(4)
	v_mfma_f32_32x32x16_bf16 v[16:31], v[200:203], v[108:111], v[16:31]
	v_permlane32_swap_b32_e32 v149, v151
	global_store_dwordx4 v244, v[144:147], s[12:13]
	global_store_dwordx4 v244, v[148:151], s[12:13] offset:16
	s_waitcnt lgkmcnt(3)
	v_mfma_f32_32x32x16_bf16 v[16:31], v[204:207], v[112:115], v[16:31]
	s_waitcnt lgkmcnt(2)
	v_mfma_f32_32x32x16_bf16 v[16:31], v[208:211], v[116:119], v[16:31]
	s_waitcnt lgkmcnt(1)
	v_mfma_f32_32x32x16_bf16 v[16:31], v[212:215], v[120:123], v[16:31]
	s_waitcnt lgkmcnt(0)
	v_mfma_f32_32x32x16_bf16 v[16:31], v[216:219], v[124:127], v[16:31]
	s_branch .Lq_ex1
.Lq_er1:
	s_waitcnt lgkmcnt(7)
	v_mfma_f32_32x32x16_bf16 v[16:31], v[188:191], v[48:51], 0
	ds_read_b128 v[188:191], v247 offset:17152
	v_mul_f32_e32 v0, v0, v155
	v_mul_f32_e32 v1, v1, v155
	v_mul_f32_e32 v2, v2, v155
	v_mul_f32_e32 v3, v3, v155
	v_mul_f32_e32 v4, v4, v155
	v_mul_f32_e32 v5, v5, v155
	s_waitcnt lgkmcnt(7)
	v_mfma_f32_32x32x16_bf16 v[16:31], v[192:195], v[52:55], v[16:31]
	ds_read_b128 v[192:195], v247 offset:17184
	v_mul_f32_e32 v6, v6, v155
	v_mul_f32_e32 v7, v7, v155
	v_mul_f32_e32 v8, v8, v155
	v_mul_f32_e32 v9, v9, v155
	v_mul_f32_e32 v10, v10, v155
	v_mul_f32_e32 v11, v11, v155
	s_waitcnt lgkmcnt(7)
	v_mfma_f32_32x32x16_bf16 v[16:31], v[196:199], v[56:59], v[16:31]
	ds_read_b128 v[196:199], v247 offset:17216
	v_mul_f32_e32 v12, v12, v155
	v_mul_f32_e32 v13, v13, v155
	v_mul_f32_e32 v14, v14, v155
	v_mul_f32_e32 v15, v15, v155
	v_mul_f32_e32 v162, v4, v134
	v_mul_f32_e32 v163, v0, v134
	s_waitcnt lgkmcnt(7)
	v_mfma_f32_32x32x16_bf16 v[16:31], v[200:203], v[60:63], v[16:31]
	ds_read_b128 v[200:203], v247 offset:17248
	v_fma_f32 v0, v0, v130, -v162
	v_fma_f32 v4, v4, v130, v163
	v_mul_f32_e32 v162, v5, v135
	v_mul_f32_e32 v163, v1, v135
	v_fma_f32 v1, v1, v131, -v162
	v_fma_f32 v5, v5, v131, v163
	s_waitcnt lgkmcnt(7)
	v_mfma_f32_32x32x16_bf16 v[16:31], v[204:207], v[64:67], v[16:31]
	ds_read_b128 v[204:207], v247 offset:17280
	v_mul_f32_e32 v162, v6, v136
	v_mul_f32_e32 v163, v2, v136
	v_fma_f32 v2, v2, v132, -v162
	v_fma_f32 v6, v6, v132, v163
	v_mul_f32_e32 v162, v7, v137
	v_mul_f32_e32 v163, v3, v137
	s_waitcnt lgkmcnt(7)
	v_mfma_f32_32x32x16_bf16 v[16:31], v[208:211], v[68:71], v[16:31]
	ds_read_b128 v[208:211], v247 offset:17312
	v_fma_f32 v3, v3, v133, -v162
	v_fma_f32 v7, v7, v133, v163
	v_mul_f32_e32 v162, v12, v158
	v_mul_f32_e32 v163, v8, v158
	v_fma_f32 v8, v8, v138, -v162
	v_fma_f32 v12, v12, v138, v163
	s_waitcnt lgkmcnt(7)
	v_mfma_f32_32x32x16_bf16 v[16:31], v[212:215], v[72:75], v[16:31]
	ds_read_b128 v[212:215], v247 offset:17344
	v_mul_f32_e32 v162, v13, v159
	v_mul_f32_e32 v163, v9, v159
	v_fma_f32 v9, v9, v139, -v162
	v_fma_f32 v13, v13, v139, v163
	v_mul_f32_e32 v162, v14, v160
	v_mul_f32_e32 v163, v10, v160
	s_waitcnt lgkmcnt(7)
	v_mfma_f32_32x32x16_bf16 v[16:31], v[216:219], v[76:79], v[16:31]
	ds_read_b128 v[216:219], v247 offset:17376
	v_fma_f32 v10, v10, v140, -v162
	v_fma_f32 v14, v14, v140, v163
	v_mul_f32_e32 v162, v15, v161
	v_mul_f32_e32 v163, v11, v161
	v_fma_f32 v11, v11, v141, -v162
	v_fma_f32 v15, v15, v141, v163
	s_waitcnt lgkmcnt(7)
	v_mfma_f32_32x32x16_bf16 v[16:31], v[188:191], v[96:99], v[16:31]
	v_mul_f32_e32 v0, s23, v0
	v_mul_f32_e32 v1, s23, v1
	v_mul_f32_e32 v2, s23, v2
	v_mul_f32_e32 v3, s23, v3
	v_mul_f32_e32 v4, s23, v4
	v_mul_f32_e32 v5, s23, v5
	s_waitcnt lgkmcnt(6)
	v_mfma_f32_32x32x16_bf16 v[16:31], v[192:195], v[100:103], v[16:31]
	v_mul_f32_e32 v6, s23, v6
	v_mul_f32_e32 v7, s23, v7
	v_mul_f32_e32 v8, s23, v8
	v_mul_f32_e32 v9, s23, v9
	v_mul_f32_e32 v10, s23, v10
	v_mul_f32_e32 v11, s23, v11
	s_waitcnt lgkmcnt(5)
	v_mfma_f32_32x32x16_bf16 v[16:31], v[196:199], v[104:107], v[16:31]
	v_mul_f32_e32 v12, s23, v12
	v_mul_f32_e32 v13, s23, v13
	v_mul_f32_e32 v14, s23, v14
	v_mul_f32_e32 v15, s23, v15
	v_cvt_pk_bf16_f32 v144, v0, v1
	v_cvt_pk_bf16_f32 v145, v2, v3
	s_waitcnt lgkmcnt(4)
	v_mfma_f32_32x32x16_bf16 v[16:31], v[200:203], v[108:111], v[16:31]
	v_cvt_pk_bf16_f32 v148, v4, v5
	v_cvt_pk_bf16_f32 v149, v6, v7
	v_cvt_pk_bf16_f32 v146, v8, v9
	v_cvt_pk_bf16_f32 v147, v10, v11
	v_cvt_pk_bf16_f32 v150, v12, v13
	v_cvt_pk_bf16_f32 v151, v14, v15
	s_waitcnt lgkmcnt(3)
	v_mfma_f32_32x32x16_bf16 v[16:31], v[204:207], v[112:115], v[16:31]
	s_nop 1
	v_permlane32_swap_b32_e32 v144, v146
	v_permlane32_swap_b32_e32 v145, v147
	v_permlane32_swap_b32_e32 v148, v150
	v_permlane32_swap_b32_e32 v149, v151
	global_store_dwordx4 v244, v[144:147], s[12:13]
	s_waitcnt lgkmcnt(2)
	v_mfma_f32_32x32x16_bf16 v[16:31], v[208:211], v[116:119], v[16:31]
	global_store_dwordx4 v244, v[148:151], s[12:13] offset:16
	s_waitcnt lgkmcnt(1)
	v_mfma_f32_32x32x16_bf16 v[16:31], v[212:215], v[120:123], v[16:31]
	s_waitcnt lgkmcnt(0)
	v_mfma_f32_32x32x16_bf16 v[16:31], v[216:219], v[124:127], v[16:31]
.Lq_ex1:
	v_mov_b32_e32 v155, v154
	s_mov_b64 s[12:13], s[14:15]
	s_mov_b32 s16, s17
	s_add_u32 s4, s4, 1
	s_waitcnt lgkmcnt(0)
	s_barrier
	s_cmp_ge_u32 s4, s5
	s_cbranch_scc1 .Lq_drain1
	s_cmp_lg_u32 s4, s6
	s_cbranch_scc1 .Lq_ns1
	s_nop 7
	s_nop 7
	s_cmp_eq_u32 s16, 2
	s_cbranch_scc1 .Lq_sr1
	v_mul_f32_e32 v16, v16, v155
	v_mul_f32_e32 v17, v17, v155
	v_mul_f32_e32 v18, v18, v155
	v_mul_f32_e32 v19, v19, v155
	v_mul_f32_e32 v20, v20, v155
	v_mul_f32_e32 v21, v21, v155
	v_mul_f32_e32 v22, v22, v155
	v_mul_f32_e32 v23, v23, v155
	v_mul_f32_e32 v24, v24, v155
	v_mul_f32_e32 v25, v25, v155
	v_mul_f32_e32 v26, v26, v155
	v_mul_f32_e32 v27, v27, v155
	v_mul_f32_e32 v28, v28, v155
	v_mul_f32_e32 v29, v29, v155
	v_mul_f32_e32 v30, v30, v155
	v_mul_f32_e32 v31, v31, v155
	v_mul_f32_e32 v16, s23, v16
	v_mul_f32_e32 v17, s23, v17
	v_mul_f32_e32 v18, s23, v18
	v_mul_f32_e32 v19, s23, v19
	v_mul_f32_e32 v20, s23, v20
	v_mul_f32_e32 v21, s23, v21
	v_mul_f32_e32 v22, s23, v22
	v_mul_f32_e32 v23, s23, v23
	v_mul_f32_e32 v24, s23, v24
	v_mul_f32_e32 v25, s23, v25
	v_mul_f32_e32 v26, s23, v26
	v_mul_f32_e32 v27, s23, v27
	v_mul_f32_e32 v28, s23, v28
	v_mul_f32_e32 v29, s23, v29
	v_mul_f32_e32 v30, s23, v30
	v_mul_f32_e32 v31, s23, v31
	v_cvt_pk_bf16_f32 v144, v16, v17
	v_cvt_pk_bf16_f32 v145, v18, v19
	v_cvt_pk_bf16_f32 v148, v20, v21
	v_cvt_pk_bf16_f32 v149, v22, v23
	v_cvt_pk_bf16_f32 v146, v24, v25
	v_cvt_pk_bf16_f32 v147, v26, v27
	v_cvt_pk_bf16_f32 v150, v28, v29
	v_cvt_pk_bf16_f32 v151, v30, v31
	s_nop 1
	v_permlane32_swap_b32_e32 v144, v146
	v_permlane32_swap_b32_e32 v145, v147
	v_permlane32_swap_b32_e32 v148, v150
	v_permlane32_swap_b32_e32 v149, v151
	global_store_dwordx4 v244, v[144:147], s[12:13]
	global_store_dwordx4 v244, v[148:151], s[12:13] offset:16
	s_branch .Lq_sx1
.Lq_sr1:
	v_mul_f32_e32 v16, v16, v155
	v_mul_f32_e32 v17, v17, v155
	v_mul_f32_e32 v18, v18, v155
	v_mul_f32_e32 v19, v19, v155
	v_mul_f32_e32 v20, v20, v155
	v_mul_f32_e32 v21, v21, v155
	v_mul_f32_e32 v22, v22, v155
	v_mul_f32_e32 v23, v23, v155
	v_mul_f32_e32 v24, v24, v155
	v_mul_f32_e32 v25, v25, v155
	v_mul_f32_e32 v26, v26, v155
	v_mul_f32_e32 v27, v27, v155
	v_mul_f32_e32 v28, v28, v155
	v_mul_f32_e32 v29, v29, v155
	v_mul_f32_e32 v30, v30, v155
	v_mul_f32_e32 v31, v31, v155
	v_mul_f32_e32 v162, v20, v134
	v_mul_f32_e32 v163, v16, v134
	v_fma_f32 v16, v16, v130, -v162
	v_fma_f32 v20, v20, v130, v163
	v_mul_f32_e32 v162, v21, v135
	v_mul_f32_e32 v163, v17, v135
	v_fma_f32 v17, v17, v131, -v162
	v_fma_f32 v21, v21, v131, v163
	v_mul_f32_e32 v162, v22, v136
	v_mul_f32_e32 v163, v18, v136
	v_fma_f32 v18, v18, v132, -v162
	v_fma_f32 v22, v22, v132, v163
	v_mul_f32_e32 v162, v23, v137
	v_mul_f32_e32 v163, v19, v137
	v_fma_f32 v19, v19, v133, -v162
	v_fma_f32 v23, v23, v133, v163
	v_mul_f32_e32 v162, v28, v158
	v_mul_f32_e32 v163, v24, v158
	v_fma_f32 v24, v24, v138, -v162
	v_fma_f32 v28, v28, v138, v163
	v_mul_f32_e32 v162, v29, v159
	v_mul_f32_e32 v163, v25, v159
	v_fma_f32 v25, v25, v139, -v162
	v_fma_f32 v29, v29, v139, v163
	v_mul_f32_e32 v162, v30, v160
	v_mul_f32_e32 v163, v26, v160
	v_fma_f32 v26, v26, v140, -v162
	v_fma_f32 v30, v30, v140, v163
	v_mul_f32_e32 v162, v31, v161
	v_mul_f32_e32 v163, v27, v161
	v_fma_f32 v27, v27, v141, -v162
	v_fma_f32 v31, v31, v141, v163
	v_mul_f32_e32 v16, s23, v16
	v_mul_f32_e32 v17, s23, v17
	v_mul_f32_e32 v18, s23, v18
	v_mul_f32_e32 v19, s23, v19
	v_mul_f32_e32 v20, s23, v20
	v_mul_f32_e32 v21, s23, v21
	v_mul_f32_e32 v22, s23, v22
	v_mul_f32_e32 v23, s23, v23
	v_mul_f32_e32 v24, s23, v24
	v_mul_f32_e32 v25, s23, v25
	v_mul_f32_e32 v26, s23, v26
	v_mul_f32_e32 v27, s23, v27
	v_mul_f32_e32 v28, s23, v28
	v_mul_f32_e32 v29, s23, v29
	v_mul_f32_e32 v30, s23, v30
	v_mul_f32_e32 v31, s23, v31
	v_cvt_pk_bf16_f32 v144, v16, v17
	v_cvt_pk_bf16_f32 v145, v18, v19
	v_cvt_pk_bf16_f32 v148, v20, v21
	v_cvt_pk_bf16_f32 v149, v22, v23
	v_cvt_pk_bf16_f32 v146, v24, v25
	v_cvt_pk_bf16_f32 v147, v26, v27
	v_cvt_pk_bf16_f32 v150, v28, v29
	v_cvt_pk_bf16_f32 v151, v30, v31
	s_nop 1
	v_permlane32_swap_b32_e32 v144, v146
	v_permlane32_swap_b32_e32 v145, v147
	v_permlane32_swap_b32_e32 v148, v150
	v_permlane32_swap_b32_e32 v149, v151
	global_store_dwordx4 v244, v[144:147], s[12:13]
	global_store_dwordx4 v244, v[148:151], s[12:13] offset:16

.Lq_drain0:
	s_nop 7
	s_nop 7
	s_cmp_eq_u32 s16, 2
	s_cbranch_scc1 .Lq_dr0
	v_mul_f32_e32 v0, v0, v155
	v_mul_f32_e32 v1, v1, v155
	v_mul_f32_e32 v2, v2, v155
	v_mul_f32_e32 v3, v3, v155
	v_mul_f32_e32 v4, v4, v155
	v_mul_f32_e32 v5, v5, v155
	v_mul_f32_e32 v6, v6, v155
	v_mul_f32_e32 v7, v7, v155
	v_mul_f32_e32 v8, v8, v155
	v_mul_f32_e32 v9, v9, v155
	v_mul_f32_e32 v10, v10, v155
	v_mul_f32_e32 v11, v11, v155
	v_mul_f32_e32 v12, v12, v155
	v_mul_f32_e32 v13, v13, v155
	v_mul_f32_e32 v14, v14, v155
	v_mul_f32_e32 v15, v15, v155
	v_mul_f32_e32 v0, s23, v0
	v_mul_f32_e32 v1, s23, v1
	v_mul_f32_e32 v2, s23, v2
	v_mul_f32_e32 v3, s23, v3
	v_mul_f32_e32 v4, s23, v4
	v_mul_f32_e32 v5, s23, v5
	v_mul_f32_e32 v6, s23, v6
	v_mul_f32_e32 v7, s23, v7
	v_mul_f32_e32 v8, s23, v8
	v_mul_f32_e32 v9, s23, v9
	v_mul_f32_e32 v10, s23, v10
	v_mul_f32_e32 v11, s23, v11
	v_mul_f32_e32 v12, s23, v12
	v_mul_f32_e32 v13, s23, v13
	v_mul_f32_e32 v14, s23, v14
	v_mul_f32_e32 v15, s23, v15
	v_cvt_pk_bf16_f32 v144, v0, v1
	v_cvt_pk_bf16_f32 v145, v2, v3
	v_cvt_pk_bf16_f32 v148, v4, v5
	v_cvt_pk_bf16_f32 v149, v6, v7
	v_cvt_pk_bf16_f32 v146, v8, v9
	v_cvt_pk_bf16_f32 v147, v10, v11
	v_cvt_pk_bf16_f32 v150, v12, v13
	v_cvt_pk_bf16_f32 v151, v14, v15
	s_nop 1
	v_permlane32_swap_b32_e32 v144, v146
	v_permlane32_swap_b32_e32 v145, v147
	v_permlane32_swap_b32_e32 v148, v150
	v_permlane32_swap_b32_e32 v149, v151
	global_store_dwordx4 v244, v[144:147], s[12:13]
	global_store_dwordx4 v244, v[148:151], s[12:13] offset:16
	s_branch .Lq_done
.Lq_dr0:
	v_mul_f32_e32 v0, v0, v155
	v_mul_f32_e32 v1, v1, v155
	v_mul_f32_e32 v2, v2, v155
	v_mul_f32_e32 v3, v3, v155
	v_mul_f32_e32 v4, v4, v155
	v_mul_f32_e32 v5, v5, v155
	v_mul_f32_e32 v6, v6, v155
	v_mul_f32_e32 v7, v7, v155
	v_mul_f32_e32 v8, v8, v155
	v_mul_f32_e32 v9, v9, v155
	v_mul_f32_e32 v10, v10, v155
	v_mul_f32_e32 v11, v11, v155
	v_mul_f32_e32 v12, v12, v155
	v_mul_f32_e32 v13, v13, v155
	v_mul_f32_e32 v14, v14, v155
	v_mul_f32_e32 v15, v15, v155
	v_mul_f32_e32 v162, v4, v134
	v_mul_f32_e32 v163, v0, v134
	v_fma_f32 v0, v0, v130, -v162
	v_fma_f32 v4, v4, v130, v163
	v_mul_f32_e32 v162, v5, v135
	v_mul_f32_e32 v163, v1, v135
	v_fma_f32 v1, v1, v131, -v162
	v_fma_f32 v5, v5, v131, v163
	v_mul_f32_e32 v162, v6, v136
	v_mul_f32_e32 v163, v2, v136
	v_fma_f32 v2, v2, v132, -v162
	v_fma_f32 v6, v6, v132, v163
	v_mul_f32_e32 v162, v7, v137
	v_mul_f32_e32 v163, v3, v137
	v_fma_f32 v3, v3, v133, -v162
	v_fma_f32 v7, v7, v133, v163
	v_mul_f32_e32 v162, v12, v158
	v_mul_f32_e32 v163, v8, v158
	v_fma_f32 v8, v8, v138, -v162
	v_fma_f32 v12, v12, v138, v163
	v_mul_f32_e32 v162, v13, v159
	v_mul_f32_e32 v163, v9, v159
	v_fma_f32 v9, v9, v139, -v162
	v_fma_f32 v13, v13, v139, v163
	v_mul_f32_e32 v162, v14, v160
	v_mul_f32_e32 v163, v10, v160
	v_fma_f32 v10, v10, v140, -v162
	v_fma_f32 v14, v14, v140, v163
	v_mul_f32_e32 v162, v15, v161
	v_mul_f32_e32 v163, v11, v161
	v_fma_f32 v11, v11, v141, -v162
	v_fma_f32 v15, v15, v141, v163
	v_mul_f32_e32 v0, s23, v0
	v_mul_f32_e32 v1, s23, v1
	v_mul_f32_e32 v2, s23, v2
	v_mul_f32_e32 v3, s23, v3
	v_mul_f32_e32 v4, s23, v4
	v_mul_f32_e32 v5, s23, v5
	v_mul_f32_e32 v6, s23, v6
	v_mul_f32_e32 v7, s23, v7
	v_mul_f32_e32 v8, s23, v8
	v_mul_f32_e32 v9, s23, v9
	v_mul_f32_e32 v10, s23, v10
	v_mul_f32_e32 v11, s23, v11
	v_mul_f32_e32 v12, s23, v12
	v_mul_f32_e32 v13, s23, v13
	v_mul_f32_e32 v14, s23, v14
	v_mul_f32_e32 v15, s23, v15
	v_cvt_pk_bf16_f32 v144, v0, v1
	v_cvt_pk_bf16_f32 v145, v2, v3
	v_cvt_pk_bf16_f32 v148, v4, v5
	v_cvt_pk_bf16_f32 v149, v6, v7
	v_cvt_pk_bf16_f32 v146, v8, v9
	v_cvt_pk_bf16_f32 v147, v10, v11
	v_cvt_pk_bf16_f32 v150, v12, v13
	v_cvt_pk_bf16_f32 v151, v14, v15
	s_nop 1
	v_permlane32_swap_b32_e32 v144, v146
	v_permlane32_swap_b32_e32 v145, v147
	v_permlane32_swap_b32_e32 v148, v150
	v_permlane32_swap_b32_e32 v149, v151
	global_store_dwordx4 v244, v[144:147], s[12:13]
	global_store_dwordx4 v244, v[148:151], s[12:13] offset:16
	s_branch .Lq_done
.Lq_drain1:
	s_nop 7
	s_nop 7
	s_cmp_eq_u32 s16, 2
	s_cbranch_scc1 .Lq_dr1
	v_mul_f32_e32 v16, v16, v155
	v_mul_f32_e32 v17, v17, v155
	v_mul_f32_e32 v18, v18, v155
	v_mul_f32_e32 v19, v19, v155
	v_mul_f32_e32 v20, v20, v155
	v_mul_f32_e32 v21, v21, v155
	v_mul_f32_e32 v22, v22, v155
	v_mul_f32_e32 v23, v23, v155
	v_mul_f32_e32 v24, v24, v155
	v_mul_f32_e32 v25, v25, v155
	v_mul_f32_e32 v26, v26, v155
	v_mul_f32_e32 v27, v27, v155
	v_mul_f32_e32 v28, v28, v155
	v_mul_f32_e32 v29, v29, v155
	v_mul_f32_e32 v30, v30, v155
	v_mul_f32_e32 v31, v31, v155
	v_mul_f32_e32 v16, s23, v16
	v_mul_f32_e32 v17, s23, v17
	v_mul_f32_e32 v18, s23, v18
	v_mul_f32_e32 v19, s23, v19
	v_mul_f32_e32 v20, s23, v20
	v_mul_f32_e32 v21, s23, v21
	v_mul_f32_e32 v22, s23, v22
	v_mul_f32_e32 v23, s23, v23
	v_mul_f32_e32 v24, s23, v24
	v_mul_f32_e32 v25, s23, v25
	v_mul_f32_e32 v26, s23, v26
	v_mul_f32_e32 v27, s23, v27
	v_mul_f32_e32 v28, s23, v28
	v_mul_f32_e32 v29, s23, v29
	v_mul_f32_e32 v30, s23, v30
	v_mul_f32_e32 v31, s23, v31
	v_cvt_pk_bf16_f32 v144, v16, v17
	v_cvt_pk_bf16_f32 v145, v18, v19
	v_cvt_pk_bf16_f32 v148, v20, v21
	v_cvt_pk_bf16_f32 v149, v22, v23
	v_cvt_pk_bf16_f32 v146, v24, v25
	v_cvt_pk_bf16_f32 v147, v26, v27
	v_cvt_pk_bf16_f32 v150, v28, v29
	v_cvt_pk_bf16_f32 v151, v30, v31
	s_nop 1
	v_permlane32_swap_b32_e32 v144, v146
	v_permlane32_swap_b32_e32 v145, v147
	v_permlane32_swap_b32_e32 v148, v150
	v_permlane32_swap_b32_e32 v149, v151
	global_store_dwordx4 v244, v[144:147], s[12:13]
	global_store_dwordx4 v244, v[148:151], s[12:13] offset:16
	s_branch .Lq_done
.Lq_dr1:
	v_mul_f32_e32 v16, v16, v155
	v_mul_f32_e32 v17, v17, v155
	v_mul_f32_e32 v18, v18, v155
	v_mul_f32_e32 v19, v19, v155
	v_mul_f32_e32 v20, v20, v155
	v_mul_f32_e32 v21, v21, v155
	v_mul_f32_e32 v22, v22, v155
	v_mul_f32_e32 v23, v23, v155
	v_mul_f32_e32 v24, v24, v155
	v_mul_f32_e32 v25, v25, v155
	v_mul_f32_e32 v26, v26, v155
	v_mul_f32_e32 v27, v27, v155
	v_mul_f32_e32 v28, v28, v155
	v_mul_f32_e32 v29, v29, v155
	v_mul_f32_e32 v30, v30, v155
	v_mul_f32_e32 v31, v31, v155
	v_mul_f32_e32 v162, v20, v134
	v_mul_f32_e32 v163, v16, v134
	v_fma_f32 v16, v16, v130, -v162
	v_fma_f32 v20, v20, v130, v163
	v_mul_f32_e32 v162, v21, v135
	v_mul_f32_e32 v163, v17, v135
	v_fma_f32 v17, v17, v131, -v162
	v_fma_f32 v21, v21, v131, v163
	v_mul_f32_e32 v162, v22, v136
	v_mul_f32_e32 v163, v18, v136
	v_fma_f32 v18, v18, v132, -v162
	v_fma_f32 v22, v22, v132, v163
	v_mul_f32_e32 v162, v23, v137
	v_mul_f32_e32 v163, v19, v137
	v_fma_f32 v19, v19, v133, -v162
	v_fma_f32 v23, v23, v133, v163
	v_mul_f32_e32 v162, v28, v158
	v_mul_f32_e32 v163, v24, v158
	v_fma_f32 v24, v24, v138, -v162
	v_fma_f32 v28, v28, v138, v163
	v_mul_f32_e32 v162, v29, v159
	v_mul_f32_e32 v163, v25, v159
	v_fma_f32 v25, v25, v139, -v162
	v_fma_f32 v29, v29, v139, v163
	v_mul_f32_e32 v162, v30, v160
	v_mul_f32_e32 v163, v26, v160
	v_fma_f32 v26, v26, v140, -v162
	v_fma_f32 v30, v30, v140, v163
	v_mul_f32_e32 v162, v31, v161
	v_mul_f32_e32 v163, v27, v161
	v_fma_f32 v27, v27, v141, -v162
	v_fma_f32 v31, v31, v141, v163
	v_mul_f32_e32 v16, s23, v16
	v_mul_f32_e32 v17, s23, v17
	v_mul_f32_e32 v18, s23, v18
	v_mul_f32_e32 v19, s23, v19
	v_mul_f32_e32 v20, s23, v20
	v_mul_f32_e32 v21, s23, v21
	v_mul_f32_e32 v22, s23, v22
	v_mul_f32_e32 v23, s23, v23
	v_mul_f32_e32 v24, s23, v24
	v_mul_f32_e32 v25, s23, v25
	v_mul_f32_e32 v26, s23, v26
	v_mul_f32_e32 v27, s23, v27
	v_mul_f32_e32 v28, s23, v28
	v_mul_f32_e32 v29, s23, v29
	v_mul_f32_e32 v30, s23, v30
	v_mul_f32_e32 v31, s23, v31
	v_cvt_pk_bf16_f32 v144, v16, v17
	v_cvt_pk_bf16_f32 v145, v18, v19
	v_cvt_pk_bf16_f32 v148, v20, v21
	v_cvt_pk_bf16_f32 v149, v22, v23
	v_cvt_pk_bf16_f32 v146, v24, v25
	v_cvt_pk_bf16_f32 v147, v26, v27
	v_cvt_pk_bf16_f32 v150, v28, v29
	v_cvt_pk_bf16_f32 v151, v30, v31
	s_nop 1
	v_permlane32_swap_b32_e32 v144, v146
	v_permlane32_swap_b32_e32 v145, v147
	v_permlane32_swap_b32_e32 v148, v150
	v_permlane32_swap_b32_e32 v149, v151
	global_store_dwordx4 v244, v[144:147], s[12:13]
	global_store_dwordx4 v244, v[148:151], s[12:13] offset:16
	s_branch .Lq_done
.Lq_done:
	s_waitcnt vmcnt(0)
	v_mov_b32_e32 v0, v143
	s_and_b64 vcc, exec, s[72:73]
	v_and_b32_e32 v250, 31, v143
	v_bfe_u32 v251, v143, 5, 1
	v_lshrrev_b32_e32 v252, 6, v143
	v_lshl_add_u32 v252, v252, 5, v250
	v_lshlrev_b32_e32 v249, 4, v251
	v_lshlrev_b32_e32 v242, 9, v252
	v_lshl_add_u32 v242, v251, 4, v242
	v_mul_u32_u24_e32 v243, 0x1440, v252
	v_lshl_add_u32 v243, v251, 5, v243
	v_lshlrev_b32_e32 v244, 11, v252
	v_lshl_add_u32 v244, v251, 5, v244
	v_lshrrev_b32_e32 v245, 5, v143
	v_mul_u32_u24_e32 v245, 528, v245
	v_and_b32_e32 v246, 31, v143
	v_lshl_add_u32 v245, v246, 4, v245
	v_lshlrev_b32_e32 v246, 4, v143
	v_add_u32_e32 v247, 0x2000, v246
	v_mul_u32_u24_e32 v248, 528, v250
	v_lshl_add_u32 v248, v251, 4, v248
	s_cmp_lg_u64 s[90:91], 0
	s_movk_i32 s0, 136
	s_cselect_b32 s7, 128, s0
	s_lshl_b32 s7, s7, 3
	v_readlane_b32 s0, v253, 0
	s_and_b32 s1, s0, 7
	s_lshl_b32 s1, s1, 5
	s_lshr_b32 s0, s0, 3
	s_add_u32 s0, s0, s1
	s_mul_i32 s4, s0, s7
	s_lshr_b32 s4, s4, 8
	s_add_u32 s0, s0, 1
	s_mul_i32 s5, s0, s7
	s_lshr_b32 s5, s5, 8
	s_lshl_b32 s0, s74, 17
	s_add_u32 s0, s0, 0xc00000
	s_add_u32 s8, s50, s0
	s_addc_u32 s9, s51, 0
	s_lshl_b32 s0, s74, 10
	s_add_u32 s22, s42, s0
	s_addc_u32 s23, s43, 0
	s_mov_b32 s65, 0xbfb8aa3b
	s_lshr_b32 s6, s4, 3
	s_add_u32 s6, s6, 1
	s_lshl_b32 s6, s6, 3
	s_min_u32 s6, s6, s5
	s_lshr_b32 s17, s4, 3
	s_lshl_b32 s17, s17, 8
	s_lshl_b32 s54, s17, 9
	s_add_u32 s54, s54, 0x1995d000
	s_add_u32 s26, s50, s54
	s_addc_u32 s27, s51, 0
	global_load_dwordx4 v[48:51], v242, s[26:27] offset:0
	global_load_dwordx4 v[52:55], v242, s[26:27] offset:32
	global_load_dwordx4 v[56:59], v242, s[26:27] offset:64
	global_load_dwordx4 v[60:63], v242, s[26:27] offset:96
	global_load_dwordx4 v[64:67], v242, s[26:27] offset:128
	global_load_dwordx4 v[68:71], v242, s[26:27] offset:160
	global_load_dwordx4 v[72:75], v242, s[26:27] offset:192
	global_load_dwordx4 v[76:79], v242, s[26:27] offset:224
	global_load_dwordx4 v[96:99], v242, s[26:27] offset:256
	global_load_dwordx4 v[100:103], v242, s[26:27] offset:288
	global_load_dwordx4 v[104:107], v242, s[26:27] offset:320
	global_load_dwordx4 v[108:111], v242, s[26:27] offset:352
	global_load_dwordx4 v[112:115], v242, s[26:27] offset:384
	global_load_dwordx4 v[116:119], v242, s[26:27] offset:416
	global_load_dwordx4 v[120:123], v242, s[26:27] offset:448
	global_load_dwordx4 v[124:127], v242, s[26:27] offset:480
	s_mov_b32 s25, s4
	s_add_u32 s0, s5, -1
	s_min_u32 s0, s25, s0
	s_and_b32 s0, s0, 7
	s_lshl_b32 s0, s0, 14
	s_add_u32 s10, s8, s0
	s_addc_u32 s11, s9, 0
	global_load_dwordx4 v[220:223], v246, s[10:11]
	global_load_dwordx4 v[224:227], v247, s[10:11]
	s_add_u32 s25, s25, 1
	s_add_u32 s0, s5, -1
	s_min_u32 s0, s25, s0
	s_and_b32 s0, s0, 7
	s_lshl_b32 s0, s0, 14
	s_add_u32 s10, s8, s0
	s_addc_u32 s11, s9, 0
	global_load_dwordx4 v[228:231], v246, s[10:11]
	global_load_dwordx4 v[238:241], v247, s[10:11]
	s_add_u32 s25, s25, 1
	s_waitcnt vmcnt(0)
	ds_write_b128 v245, v[220:223]
	ds_write_b128 v245, v[224:227] offset:8448
	s_add_u32 s0, s5, -1
	s_min_u32 s0, s25, s0
	s_and_b32 s0, s0, 7
	s_lshl_b32 s0, s0, 14
	s_add_u32 s10, s8, s0
	s_addc_u32 s11, s9, 0
	global_load_dwordx4 v[220:223], v246, s[10:11]
	global_load_dwordx4 v[224:227], v247, s[10:11]
	s_add_u32 s25, s25, 1
	global_load_dword v179, v249, s[22:23]
	global_load_dword v128, v249, s[22:23]
	s_add_u32 s0, s4, 0
	s_and_b32 s0, s0, 7
	s_lshl_b32 s0, s0, 7
	s_add_u32 s30, s22, s0
	s_addc_u32 s31, s23, 0
	global_load_dwordx4 v[144:147], v249, s[30:31] offset:0
	global_load_dwordx4 v[148:151], v249, s[30:31] offset:32
	global_load_dwordx4 v[152:155], v249, s[30:31] offset:64
	global_load_dwordx4 v[156:159], v249, s[30:31] offset:96
	global_load_dword v179, v249, s[22:23]
	global_load_dword v128, v249, s[22:23]
	s_waitcnt lgkmcnt(0)
	s_barrier
	s_mov_b32 s16, 0
.Lc_loop:
	s_waitcnt vmcnt(18)
	ds_write_b128 v245, v[228:231] offset:16896
	ds_write_b128 v245, v[238:241] offset:25344
	s_add_u32 s0, s5, -1
	s_min_u32 s0, s25, s0
	s_and_b32 s0, s0, 7
	s_lshl_b32 s0, s0, 14
	s_add_u32 s10, s8, s0
	s_addc_u32 s11, s9, 0
	global_load_dwordx4 v[228:231], v246, s[10:11]
	global_load_dwordx4 v[238:241], v247, s[10:11]
	s_add_u32 s25, s25, 1
	s_and_b32 s0, s4, 7
	s_lshl_b32 s0, s0, 6
	s_mul_i32 s1, s17, 5184
	s_add_u32 s1, s1, s0
	s_add_u32 s1, s1, 0x5cbe240
	s_add_u32 s20, s50, s1
	s_addc_u32 s21, s51, 0
	s_lshl_b32 s1, s17, 11
	s_add_u32 s1, s1, s0
	s_add_u32 s1, s1, 0x18bd600
	s_add_u32 s14, s50, s1
	s_addc_u32 s15, s51, 0
	ds_read_b128 v[188:191], v248 offset:0
	ds_read_b128 v[192:195], v248 offset:32
	ds_read_b128 v[196:199], v248 offset:64
	ds_read_b128 v[200:203], v248 offset:96
	ds_read_b128 v[204:207], v248 offset:128
	ds_read_b128 v[208:211], v248 offset:160
	ds_read_b128 v[212:215], v248 offset:192
	ds_read_b128 v[216:219], v248 offset:224
	global_load_dwordx4 v[160:163], v243, s[20:21]
	global_load_dwordx4 v[164:167], v243, s[20:21] offset:16
	s_waitcnt vmcnt(6)
	s_cmp_eq_u32 s16, 0
	s_cbranch_scc0 .Lc_ep0
	s_waitcnt lgkmcnt(7)
	v_mfma_f32_32x32x16_bf16 v[0:15], v[188:191], v[48:51], v[144:159]
	ds_read_b128 v[188:191], v248 offset:256
	s_add_u32 s0, s4, 1
	s_waitcnt lgkmcnt(7)
	v_mfma_f32_32x32x16_bf16 v[0:15], v[192:195], v[52:55], v[0:15]
	ds_read_b128 v[192:195], v248 offset:288
	s_and_b32 s0, s0, 7
	s_waitcnt lgkmcnt(7)
	v_mfma_f32_32x32x16_bf16 v[0:15], v[196:199], v[56:59], v[0:15]
	ds_read_b128 v[196:199], v248 offset:320
	s_lshl_b32 s0, s0, 7
	s_waitcnt lgkmcnt(7)
	v_mfma_f32_32x32x16_bf16 v[0:15], v[200:203], v[60:63], v[0:15]
	ds_read_b128 v[200:203], v248 offset:352
	s_add_u32 s30, s22, s0
	s_waitcnt lgkmcnt(7)
	v_mfma_f32_32x32x16_bf16 v[0:15], v[204:207], v[64:67], v[0:15]
	ds_read_b128 v[204:207], v248 offset:384
	s_addc_u32 s31, s23, 0
	s_waitcnt lgkmcnt(7)
	v_mfma_f32_32x32x16_bf16 v[0:15], v[208:211], v[68:71], v[0:15]
	ds_read_b128 v[208:211], v248 offset:416
	global_load_dwordx4 v[144:147], v249, s[30:31] offset:0
	s_waitcnt lgkmcnt(7)
	v_mfma_f32_32x32x16_bf16 v[0:15], v[212:215], v[72:75], v[0:15]
	ds_read_b128 v[212:215], v248 offset:448
	global_load_dwordx4 v[148:151], v249, s[30:31] offset:32
	s_waitcnt lgkmcnt(7)
	v_mfma_f32_32x32x16_bf16 v[0:15], v[216:219], v[76:79], v[0:15]
	ds_read_b128 v[216:219], v248 offset:480
	global_load_dwordx4 v[152:155], v249, s[30:31] offset:64
	s_waitcnt lgkmcnt(7)
	v_mfma_f32_32x32x16_bf16 v[0:15], v[188:191], v[96:99], v[0:15]
	global_load_dwordx4 v[156:159], v249, s[30:31] offset:96
	s_waitcnt lgkmcnt(6)
	v_mfma_f32_32x32x16_bf16 v[0:15], v[192:195], v[100:103], v[0:15]
	global_load_dword v179, v249, s[22:23]
	s_waitcnt lgkmcnt(5)
	v_mfma_f32_32x32x16_bf16 v[0:15], v[196:199], v[104:107], v[0:15]
	global_load_dword v128, v249, s[22:23]
	s_waitcnt lgkmcnt(4)
	v_mfma_f32_32x32x16_bf16 v[0:15], v[200:203], v[108:111], v[0:15]
	s_waitcnt lgkmcnt(3)
	v_mfma_f32_32x32x16_bf16 v[0:15], v[204:207], v[112:115], v[0:15]
	s_waitcnt lgkmcnt(2)
	v_mfma_f32_32x32x16_bf16 v[0:15], v[208:211], v[116:119], v[0:15]
	s_waitcnt lgkmcnt(1)
	v_mfma_f32_32x32x16_bf16 v[0:15], v[212:215], v[120:123], v[0:15]
	s_waitcnt lgkmcnt(0)
	v_mfma_f32_32x32x16_bf16 v[0:15], v[216:219], v[124:127], v[0:15]
	s_branch .Lc_ex0
.Lc_ep0:
	s_waitcnt lgkmcnt(7)
	v_mfma_f32_32x32x16_bf16 v[0:15], v[188:191], v[48:51], v[144:159]
	ds_read_b128 v[188:191], v248 offset:256
	s_add_u32 s0, s4, 1
	s_and_b32 s0, s0, 7
	s_lshl_b32 s0, s0, 7
	s_add_u32 s30, s22, s0
	s_addc_u32 s31, s23, 0
	global_load_dwordx4 v[144:147], v249, s[30:31] offset:0
	global_load_dwordx4 v[148:151], v249, s[30:31] offset:32
	global_load_dwordx4 v[152:155], v249, s[30:31] offset:64
	global_load_dwordx4 v[156:159], v249, s[30:31] offset:96
	s_waitcnt vmcnt(14)
	v_cvt_pk_bf16_f32 v130, v16, v17
	s_waitcnt lgkmcnt(7)
	v_mfma_f32_32x32x16_bf16 v[0:15], v[192:195], v[52:55], v[0:15]
	ds_read_b128 v[192:195], v248 offset:288
	v_cvt_pk_bf16_f32 v131, v18, v19
	v_cvt_pk_bf16_f32 v134, v20, v21
	v_cvt_pk_bf16_f32 v135, v22, v23
	v_cvt_pk_bf16_f32 v132, v24, v25
	v_cvt_pk_bf16_f32 v133, v26, v27
	v_cvt_pk_bf16_f32 v136, v28, v29
	v_cvt_pk_bf16_f32 v137, v30, v31
	s_nop 1
	v_permlane32_swap_b32_e32 v130, v132
	v_permlane32_swap_b32_e32 v131, v133
	v_permlane32_swap_b32_e32 v134, v136
	s_waitcnt lgkmcnt(7)
	v_mfma_f32_32x32x16_bf16 v[0:15], v[196:199], v[56:59], v[0:15]
	ds_read_b128 v[196:199], v248 offset:320
	v_permlane32_swap_b32_e32 v135, v137
	v_lshlrev_b32_e32 v138, 16, v170
	v_and_b32_e32 v139, 0xffff0000, v170
	v_lshlrev_b32_e32 v140, 16, v171
	v_and_b32_e32 v141, 0xffff0000, v171
	v_mul_f32_e32 v181, s65, v138
	v_mul_f32_e32 v182, s65, v139
	v_mul_f32_e32 v183, s65, v140
	v_mul_f32_e32 v184, s65, v141
	v_exp_f32_e32 v181, v181
	v_exp_f32_e32 v182, v182
	s_waitcnt lgkmcnt(7)
	v_mfma_f32_32x32x16_bf16 v[0:15], v[200:203], v[60:63], v[0:15]
	ds_read_b128 v[200:203], v248 offset:352
	v_exp_f32_e32 v183, v183
	v_exp_f32_e32 v184, v184
	v_add_f32_e32 v181, 1.0, v181
	v_add_f32_e32 v182, 1.0, v182
	v_add_f32_e32 v183, 1.0, v183
	v_add_f32_e32 v184, 1.0, v184
	v_rcp_f32_e32 v181, v181
	v_rcp_f32_e32 v182, v182
	v_rcp_f32_e32 v183, v183
	v_rcp_f32_e32 v184, v184
	s_nop 0
	s_waitcnt lgkmcnt(7)
	v_mfma_f32_32x32x16_bf16 v[0:15], v[204:207], v[64:67], v[0:15]
	ds_read_b128 v[204:207], v248 offset:384
	v_mul_f32_e32 v138, v138, v181
	v_mul_f32_e32 v139, v139, v182
	v_mul_f32_e32 v140, v140, v183
	v_mul_f32_e32 v141, v141, v184
	v_lshlrev_b32_e32 v181, 16, v130
	v_and_b32_e32 v182, 0xffff0000, v130
	v_lshlrev_b32_e32 v183, 16, v131
	v_and_b32_e32 v184, 0xffff0000, v131
	v_mul_f32_e32 v181, v181, v138
	v_mul_f32_e32 v182, v182, v139
	v_mul_f32_e32 v183, v183, v140
	s_waitcnt lgkmcnt(7)
	v_mfma_f32_32x32x16_bf16 v[0:15], v[208:211], v[68:71], v[0:15]
	ds_read_b128 v[208:211], v248 offset:416
	v_mul_f32_e32 v184, v184, v141
	v_cvt_pk_bf16_f32 v130, v181, v182
	v_cvt_pk_bf16_f32 v131, v183, v184
	v_lshlrev_b32_e32 v138, 16, v172
	v_and_b32_e32 v139, 0xffff0000, v172
	v_lshlrev_b32_e32 v140, 16, v173
	v_and_b32_e32 v141, 0xffff0000, v173
	v_mul_f32_e32 v181, s65, v138
	v_mul_f32_e32 v182, s65, v139
	v_mul_f32_e32 v183, s65, v140
	v_mul_f32_e32 v184, s65, v141
	s_waitcnt lgkmcnt(7)
	v_mfma_f32_32x32x16_bf16 v[0:15], v[212:215], v[72:75], v[0:15]
	ds_read_b128 v[212:215], v248 offset:448
	v_exp_f32_e32 v181, v181
	v_exp_f32_e32 v182, v182
	v_exp_f32_e32 v183, v183
	v_exp_f32_e32 v184, v184
	v_add_f32_e32 v181, 1.0, v181
	v_add_f32_e32 v182, 1.0, v182
	v_add_f32_e32 v183, 1.0, v183
	v_add_f32_e32 v184, 1.0, v184
	v_rcp_f32_e32 v181, v181
	v_rcp_f32_e32 v182, v182
	v_rcp_f32_e32 v183, v183
	s_waitcnt lgkmcnt(7)
	v_mfma_f32_32x32x16_bf16 v[0:15], v[216:219], v[76:79], v[0:15]
	ds_read_b128 v[216:219], v248 offset:480
	v_rcp_f32_e32 v184, v184
	s_nop 0
	v_mul_f32_e32 v138, v138, v181
	v_mul_f32_e32 v139, v139, v182
	v_mul_f32_e32 v140, v140, v183
	v_mul_f32_e32 v141, v141, v184
	v_lshlrev_b32_e32 v181, 16, v132
	v_and_b32_e32 v182, 0xffff0000, v132
	v_lshlrev_b32_e32 v183, 16, v133
	v_and_b32_e32 v184, 0xffff0000, v133
	v_mul_f32_e32 v181, v181, v138
	s_waitcnt lgkmcnt(7)
	v_mfma_f32_32x32x16_bf16 v[0:15], v[188:191], v[96:99], v[0:15]
	v_mul_f32_e32 v182, v182, v139
	v_mul_f32_e32 v183, v183, v140
	v_mul_f32_e32 v184, v184, v141
	v_cvt_pk_bf16_f32 v132, v181, v182
	v_cvt_pk_bf16_f32 v133, v183, v184
	v_lshlrev_b32_e32 v138, 16, v174
	v_and_b32_e32 v139, 0xffff0000, v174
	v_lshlrev_b32_e32 v140, 16, v175
	v_and_b32_e32 v141, 0xffff0000, v175
	v_mul_f32_e32 v181, s65, v138
	v_mul_f32_e32 v182, s65, v139
	s_waitcnt lgkmcnt(6)
	v_mfma_f32_32x32x16_bf16 v[0:15], v[192:195], v[100:103], v[0:15]
	v_mul_f32_e32 v183, s65, v140
	v_mul_f32_e32 v184, s65, v141
	v_exp_f32_e32 v181, v181
	v_exp_f32_e32 v182, v182
	v_exp_f32_e32 v183, v183
	v_exp_f32_e32 v184, v184
	v_add_f32_e32 v181, 1.0, v181
	v_add_f32_e32 v182, 1.0, v182
	v_add_f32_e32 v183, 1.0, v183
	v_add_f32_e32 v184, 1.0, v184
	v_rcp_f32_e32 v181, v181
	s_waitcnt lgkmcnt(5)
	v_mfma_f32_32x32x16_bf16 v[0:15], v[196:199], v[104:107], v[0:15]
	v_rcp_f32_e32 v182, v182
	v_rcp_f32_e32 v183, v183
	v_rcp_f32_e32 v184, v184
	s_nop 0
	v_mul_f32_e32 v138, v138, v181
	v_mul_f32_e32 v139, v139, v182
	v_mul_f32_e32 v140, v140, v183
	v_mul_f32_e32 v141, v141, v184
	v_lshlrev_b32_e32 v181, 16, v134
	v_and_b32_e32 v182, 0xffff0000, v134
	v_lshlrev_b32_e32 v183, 16, v135
	s_waitcnt lgkmcnt(4)
	v_mfma_f32_32x32x16_bf16 v[0:15], v[200:203], v[108:111], v[0:15]
	v_and_b32_e32 v184, 0xffff0000, v135
	v_mul_f32_e32 v181, v181, v138
	v_mul_f32_e32 v182, v182, v139
	v_mul_f32_e32 v183, v183, v140
	v_mul_f32_e32 v184, v184, v141
	v_cvt_pk_bf16_f32 v134, v181, v182
	v_cvt_pk_bf16_f32 v135, v183, v184
	v_lshlrev_b32_e32 v138, 16, v176
	v_and_b32_e32 v139, 0xffff0000, v176
	v_lshlrev_b32_e32 v140, 16, v177
	v_and_b32_e32 v141, 0xffff0000, v177
	s_waitcnt lgkmcnt(3)
	v_mfma_f32_32x32x16_bf16 v[0:15], v[204:207], v[112:115], v[0:15]
	v_mul_f32_e32 v181, s65, v138
	v_mul_f32_e32 v182, s65, v139
	v_mul_f32_e32 v183, s65, v140
	v_mul_f32_e32 v184, s65, v141
	v_exp_f32_e32 v181, v181
	v_exp_f32_e32 v182, v182
	v_exp_f32_e32 v183, v183
	v_exp_f32_e32 v184, v184
	v_add_f32_e32 v181, 1.0, v181
	v_add_f32_e32 v182, 1.0, v182
	v_add_f32_e32 v183, 1.0, v183
	s_waitcnt lgkmcnt(2)
	v_mfma_f32_32x32x16_bf16 v[0:15], v[208:211], v[116:119], v[0:15]
	v_add_f32_e32 v184, 1.0, v184
	v_rcp_f32_e32 v181, v181
	v_rcp_f32_e32 v182, v182
	v_rcp_f32_e32 v183, v183
	v_rcp_f32_e32 v184, v184
	s_nop 0
	v_mul_f32_e32 v138, v138, v181
	v_mul_f32_e32 v139, v139, v182
	v_mul_f32_e32 v140, v140, v183
	v_mul_f32_e32 v141, v141, v184
	v_lshlrev_b32_e32 v181, 16, v136
	s_waitcnt lgkmcnt(1)
	v_mfma_f32_32x32x16_bf16 v[0:15], v[212:215], v[120:123], v[0:15]
	v_and_b32_e32 v182, 0xffff0000, v136
	v_lshlrev_b32_e32 v183, 16, v137
	v_and_b32_e32 v184, 0xffff0000, v137
	v_mul_f32_e32 v181, v181, v138
	v_mul_f32_e32 v182, v182, v139
	v_mul_f32_e32 v183, v183, v140
	v_mul_f32_e32 v184, v184, v141
	v_cvt_pk_bf16_f32 v136, v181, v182
	v_cvt_pk_bf16_f32 v137, v183, v184
	global_store_dwordx4 v244, v[130:133], s[12:13]
	global_store_dwordx4 v244, v[134:137], s[12:13] offset:16
	s_waitcnt lgkmcnt(0)
	v_mfma_f32_32x32x16_bf16 v[0:15], v[216:219], v[124:127], v[0:15]

.Lc_ns0:
	s_waitcnt vmcnt(18)
	ds_write_b128 v245, v[220:223] offset:0
	ds_write_b128 v245, v[224:227] offset:8448
	s_add_u32 s0, s5, -1
	s_min_u32 s0, s25, s0
	s_and_b32 s0, s0, 7
	s_lshl_b32 s0, s0, 14
	s_add_u32 s10, s8, s0
	s_addc_u32 s11, s9, 0
	global_load_dwordx4 v[220:223], v246, s[10:11]
	global_load_dwordx4 v[224:227], v247, s[10:11]
	s_add_u32 s25, s25, 1
	s_and_b32 s0, s4, 7
	s_lshl_b32 s0, s0, 6
	s_mul_i32 s1, s17, 5184
	s_add_u32 s1, s1, s0
	s_add_u32 s1, s1, 0x5cbe240
	s_add_u32 s20, s50, s1
	s_addc_u32 s21, s51, 0
	s_lshl_b32 s1, s17, 11
	s_add_u32 s1, s1, s0
	s_add_u32 s1, s1, 0x18bd600
	s_add_u32 s14, s50, s1
	s_addc_u32 s15, s51, 0
	ds_read_b128 v[188:191], v248 offset:16896
	ds_read_b128 v[192:195], v248 offset:16928
	ds_read_b128 v[196:199], v248 offset:16960
	ds_read_b128 v[200:203], v248 offset:16992
	ds_read_b128 v[204:207], v248 offset:17024
	ds_read_b128 v[208:211], v248 offset:17056
	ds_read_b128 v[212:215], v248 offset:17088
	ds_read_b128 v[216:219], v248 offset:17120
	global_load_dwordx4 v[170:173], v243, s[20:21]
	global_load_dwordx4 v[174:177], v243, s[20:21] offset:16
	s_waitcnt vmcnt(6)
	s_cmp_eq_u32 s16, 0
	s_cbranch_scc0 .Lc_ep1
	s_waitcnt lgkmcnt(7)
	v_mfma_f32_32x32x16_bf16 v[16:31], v[188:191], v[48:51], v[144:159]
	ds_read_b128 v[188:191], v248 offset:17152
	s_add_u32 s0, s4, 1
	s_waitcnt lgkmcnt(7)
	v_mfma_f32_32x32x16_bf16 v[16:31], v[192:195], v[52:55], v[16:31]
	ds_read_b128 v[192:195], v248 offset:17184
	s_and_b32 s0, s0, 7
	s_waitcnt lgkmcnt(7)
	v_mfma_f32_32x32x16_bf16 v[16:31], v[196:199], v[56:59], v[16:31]
	ds_read_b128 v[196:199], v248 offset:17216
	s_lshl_b32 s0, s0, 7
	s_waitcnt lgkmcnt(7)
	v_mfma_f32_32x32x16_bf16 v[16:31], v[200:203], v[60:63], v[16:31]
	ds_read_b128 v[200:203], v248 offset:17248
	s_add_u32 s30, s22, s0
	s_waitcnt lgkmcnt(7)
	v_mfma_f32_32x32x16_bf16 v[16:31], v[204:207], v[64:67], v[16:31]
	ds_read_b128 v[204:207], v248 offset:17280
	s_addc_u32 s31, s23, 0
	s_waitcnt lgkmcnt(7)
	v_mfma_f32_32x32x16_bf16 v[16:31], v[208:211], v[68:71], v[16:31]
	ds_read_b128 v[208:211], v248 offset:17312
	global_load_dwordx4 v[144:147], v249, s[30:31] offset:0
	s_waitcnt lgkmcnt(7)
	v_mfma_f32_32x32x16_bf16 v[16:31], v[212:215], v[72:75], v[16:31]
	ds_read_b128 v[212:215], v248 offset:17344
	global_load_dwordx4 v[148:151], v249, s[30:31] offset:32
	s_waitcnt lgkmcnt(7)
	v_mfma_f32_32x32x16_bf16 v[16:31], v[216:219], v[76:79], v[16:31]
	ds_read_b128 v[216:219], v248 offset:17376
	global_load_dwordx4 v[152:155], v249, s[30:31] offset:64
	s_waitcnt lgkmcnt(7)
	v_mfma_f32_32x32x16_bf16 v[16:31], v[188:191], v[96:99], v[16:31]
	global_load_dwordx4 v[156:159], v249, s[30:31] offset:96
	s_waitcnt lgkmcnt(6)
	v_mfma_f32_32x32x16_bf16 v[16:31], v[192:195], v[100:103], v[16:31]
	global_load_dword v179, v249, s[22:23]
	s_waitcnt lgkmcnt(5)
	v_mfma_f32_32x32x16_bf16 v[16:31], v[196:199], v[104:107], v[16:31]
	global_load_dword v128, v249, s[22:23]
	s_waitcnt lgkmcnt(4)
	v_mfma_f32_32x32x16_bf16 v[16:31], v[200:203], v[108:111], v[16:31]
	s_waitcnt lgkmcnt(3)
	v_mfma_f32_32x32x16_bf16 v[16:31], v[204:207], v[112:115], v[16:31]
	s_waitcnt lgkmcnt(2)
	v_mfma_f32_32x32x16_bf16 v[16:31], v[208:211], v[116:119], v[16:31]
	s_waitcnt lgkmcnt(1)
	v_mfma_f32_32x32x16_bf16 v[16:31], v[212:215], v[120:123], v[16:31]
	s_waitcnt lgkmcnt(0)
	v_mfma_f32_32x32x16_bf16 v[16:31], v[216:219], v[124:127], v[16:31]
	s_branch .Lc_ex1
.Lc_ep1:
	s_waitcnt lgkmcnt(7)
	v_mfma_f32_32x32x16_bf16 v[16:31], v[188:191], v[48:51], v[144:159]
	ds_read_b128 v[188:191], v248 offset:17152
	s_add_u32 s0, s4, 1
	s_and_b32 s0, s0, 7
	s_lshl_b32 s0, s0, 7
	s_add_u32 s30, s22, s0
	s_addc_u32 s31, s23, 0
	global_load_dwordx4 v[144:147], v249, s[30:31] offset:0
	global_load_dwordx4 v[148:151], v249, s[30:31] offset:32
	global_load_dwordx4 v[152:155], v249, s[30:31] offset:64
	global_load_dwordx4 v[156:159], v249, s[30:31] offset:96
	s_waitcnt vmcnt(14)
	v_cvt_pk_bf16_f32 v130, v0, v1
	s_waitcnt lgkmcnt(7)
	v_mfma_f32_32x32x16_bf16 v[16:31], v[192:195], v[52:55], v[16:31]
	ds_read_b128 v[192:195], v248 offset:17184
	v_cvt_pk_bf16_f32 v131, v2, v3
	v_cvt_pk_bf16_f32 v134, v4, v5
	v_cvt_pk_bf16_f32 v135, v6, v7
	v_cvt_pk_bf16_f32 v132, v8, v9
	v_cvt_pk_bf16_f32 v133, v10, v11
	v_cvt_pk_bf16_f32 v136, v12, v13
	v_cvt_pk_bf16_f32 v137, v14, v15
	s_nop 1
	v_permlane32_swap_b32_e32 v130, v132
	v_permlane32_swap_b32_e32 v131, v133
	v_permlane32_swap_b32_e32 v134, v136
	s_waitcnt lgkmcnt(7)
	v_mfma_f32_32x32x16_bf16 v[16:31], v[196:199], v[56:59], v[16:31]
	ds_read_b128 v[196:199], v248 offset:17216
	v_permlane32_swap_b32_e32 v135, v137
	v_lshlrev_b32_e32 v138, 16, v160
	v_and_b32_e32 v139, 0xffff0000, v160
	v_lshlrev_b32_e32 v140, 16, v161
	v_and_b32_e32 v141, 0xffff0000, v161
	v_mul_f32_e32 v181, s65, v138
	v_mul_f32_e32 v182, s65, v139
	v_mul_f32_e32 v183, s65, v140
	v_mul_f32_e32 v184, s65, v141
	v_exp_f32_e32 v181, v181
	v_exp_f32_e32 v182, v182
	s_waitcnt lgkmcnt(7)
	v_mfma_f32_32x32x16_bf16 v[16:31], v[200:203], v[60:63], v[16:31]
	ds_read_b128 v[200:203], v248 offset:17248
	v_exp_f32_e32 v183, v183
	v_exp_f32_e32 v184, v184
	v_add_f32_e32 v181, 1.0, v181
	v_add_f32_e32 v182, 1.0, v182
	v_add_f32_e32 v183, 1.0, v183
	v_add_f32_e32 v184, 1.0, v184
	v_rcp_f32_e32 v181, v181
	v_rcp_f32_e32 v182, v182
	v_rcp_f32_e32 v183, v183
	v_rcp_f32_e32 v184, v184
	s_nop 0
	s_waitcnt lgkmcnt(7)
	v_mfma_f32_32x32x16_bf16 v[16:31], v[204:207], v[64:67], v[16:31]
	ds_read_b128 v[204:207], v248 offset:17280
	v_mul_f32_e32 v138, v138, v181
	v_mul_f32_e32 v139, v139, v182
	v_mul_f32_e32 v140, v140, v183
	v_mul_f32_e32 v141, v141, v184
	v_lshlrev_b32_e32 v181, 16, v130
	v_and_b32_e32 v182, 0xffff0000, v130
	v_lshlrev_b32_e32 v183, 16, v131
	v_and_b32_e32 v184, 0xffff0000, v131
	v_mul_f32_e32 v181, v181, v138
	v_mul_f32_e32 v182, v182, v139
	v_mul_f32_e32 v183, v183, v140
	s_waitcnt lgkmcnt(7)
	v_mfma_f32_32x32x16_bf16 v[16:31], v[208:211], v[68:71], v[16:31]
	ds_read_b128 v[208:211], v248 offset:17312
	v_mul_f32_e32 v184, v184, v141
	v_cvt_pk_bf16_f32 v130, v181, v182
	v_cvt_pk_bf16_f32 v131, v183, v184
	v_lshlrev_b32_e32 v138, 16, v162
	v_and_b32_e32 v139, 0xffff0000, v162
	v_lshlrev_b32_e32 v140, 16, v163
	v_and_b32_e32 v141, 0xffff0000, v163
	v_mul_f32_e32 v181, s65, v138
	v_mul_f32_e32 v182, s65, v139
	v_mul_f32_e32 v183, s65, v140
	v_mul_f32_e32 v184, s65, v141
	s_waitcnt lgkmcnt(7)
	v_mfma_f32_32x32x16_bf16 v[16:31], v[212:215], v[72:75], v[16:31]
	ds_read_b128 v[212:215], v248 offset:17344
	v_exp_f32_e32 v181, v181
	v_exp_f32_e32 v182, v182
	v_exp_f32_e32 v183, v183
	v_exp_f32_e32 v184, v184
	v_add_f32_e32 v181, 1.0, v181
	v_add_f32_e32 v182, 1.0, v182
	v_add_f32_e32 v183, 1.0, v183
	v_add_f32_e32 v184, 1.0, v184
	v_rcp_f32_e32 v181, v181
	v_rcp_f32_e32 v182, v182
	v_rcp_f32_e32 v183, v183
	s_waitcnt lgkmcnt(7)
	v_mfma_f32_32x32x16_bf16 v[16:31], v[216:219], v[76:79], v[16:31]
	ds_read_b128 v[216:219], v248 offset:17376
	v_rcp_f32_e32 v184, v184
	s_nop 0
	v_mul_f32_e32 v138, v138, v181
	v_mul_f32_e32 v139, v139, v182
	v_mul_f32_e32 v140, v140, v183
	v_mul_f32_e32 v141, v141, v184
	v_lshlrev_b32_e32 v181, 16, v132
	v_and_b32_e32 v182, 0xffff0000, v132
	v_lshlrev_b32_e32 v183, 16, v133
	v_and_b32_e32 v184, 0xffff0000, v133
	v_mul_f32_e32 v181, v181, v138
	s_waitcnt lgkmcnt(7)
	v_mfma_f32_32x32x16_bf16 v[16:31], v[188:191], v[96:99], v[16:31]
	v_mul_f32_e32 v182, v182, v139
	v_mul_f32_e32 v183, v183, v140
	v_mul_f32_e32 v184, v184, v141
	v_cvt_pk_bf16_f32 v132, v181, v182
	v_cvt_pk_bf16_f32 v133, v183, v184
	v_lshlrev_b32_e32 v138, 16, v164
	v_and_b32_e32 v139, 0xffff0000, v164
	v_lshlrev_b32_e32 v140, 16, v165
	v_and_b32_e32 v141, 0xffff0000, v165
	v_mul_f32_e32 v181, s65, v138
	v_mul_f32_e32 v182, s65, v139
	s_waitcnt lgkmcnt(6)
	v_mfma_f32_32x32x16_bf16 v[16:31], v[192:195], v[100:103], v[16:31]
	v_mul_f32_e32 v183, s65, v140
	v_mul_f32_e32 v184, s65, v141
	v_exp_f32_e32 v181, v181
	v_exp_f32_e32 v182, v182
	v_exp_f32_e32 v183, v183
	v_exp_f32_e32 v184, v184
	v_add_f32_e32 v181, 1.0, v181
	v_add_f32_e32 v182, 1.0, v182
	v_add_f32_e32 v183, 1.0, v183
	v_add_f32_e32 v184, 1.0, v184
	v_rcp_f32_e32 v181, v181
	s_waitcnt lgkmcnt(5)
	v_mfma_f32_32x32x16_bf16 v[16:31], v[196:199], v[104:107], v[16:31]
	v_rcp_f32_e32 v182, v182
	v_rcp_f32_e32 v183, v183
	v_rcp_f32_e32 v184, v184
	s_nop 0
	v_mul_f32_e32 v138, v138, v181
	v_mul_f32_e32 v139, v139, v182
	v_mul_f32_e32 v140, v140, v183
	v_mul_f32_e32 v141, v141, v184
	v_lshlrev_b32_e32 v181, 16, v134
	v_and_b32_e32 v182, 0xffff0000, v134
	v_lshlrev_b32_e32 v183, 16, v135
	s_waitcnt lgkmcnt(4)
	v_mfma_f32_32x32x16_bf16 v[16:31], v[200:203], v[108:111], v[16:31]
	v_and_b32_e32 v184, 0xffff0000, v135
	v_mul_f32_e32 v181, v181, v138
	v_mul_f32_e32 v182, v182, v139
	v_mul_f32_e32 v183, v183, v140
	v_mul_f32_e32 v184, v184, v141
	v_cvt_pk_bf16_f32 v134, v181, v182
	v_cvt_pk_bf16_f32 v135, v183, v184
	v_lshlrev_b32_e32 v138, 16, v166
	v_and_b32_e32 v139, 0xffff0000, v166
	v_lshlrev_b32_e32 v140, 16, v167
	v_and_b32_e32 v141, 0xffff0000, v167
	s_waitcnt lgkmcnt(3)
	v_mfma_f32_32x32x16_bf16 v[16:31], v[204:207], v[112:115], v[16:31]
	v_mul_f32_e32 v181, s65, v138
	v_mul_f32_e32 v182, s65, v139
	v_mul_f32_e32 v183, s65, v140
	v_mul_f32_e32 v184, s65, v141
	v_exp_f32_e32 v181, v181
	v_exp_f32_e32 v182, v182
	v_exp_f32_e32 v183, v183
	v_exp_f32_e32 v184, v184
	v_add_f32_e32 v181, 1.0, v181
	v_add_f32_e32 v182, 1.0, v182
	v_add_f32_e32 v183, 1.0, v183
	s_waitcnt lgkmcnt(2)
	v_mfma_f32_32x32x16_bf16 v[16:31], v[208:211], v[116:119], v[16:31]
	v_add_f32_e32 v184, 1.0, v184
	v_rcp_f32_e32 v181, v181
	v_rcp_f32_e32 v182, v182
	v_rcp_f32_e32 v183, v183
	v_rcp_f32_e32 v184, v184
	s_nop 0
	v_mul_f32_e32 v138, v138, v181
	v_mul_f32_e32 v139, v139, v182
	v_mul_f32_e32 v140, v140, v183
	v_mul_f32_e32 v141, v141, v184
	v_lshlrev_b32_e32 v181, 16, v136
	s_waitcnt lgkmcnt(1)
	v_mfma_f32_32x32x16_bf16 v[16:31], v[212:215], v[120:123], v[16:31]
	v_and_b32_e32 v182, 0xffff0000, v136
	v_lshlrev_b32_e32 v183, 16, v137
	v_and_b32_e32 v184, 0xffff0000, v137
	v_mul_f32_e32 v181, v181, v138
	v_mul_f32_e32 v182, v182, v139
	v_mul_f32_e32 v183, v183, v140
	v_mul_f32_e32 v184, v184, v141
	v_cvt_pk_bf16_f32 v136, v181, v182
	v_cvt_pk_bf16_f32 v137, v183, v184
	global_store_dwordx4 v244, v[130:133], s[12:13]
	global_store_dwordx4 v244, v[134:137], s[12:13] offset:16
	s_waitcnt lgkmcnt(0)
	v_mfma_f32_32x32x16_bf16 v[16:31], v[216:219], v[124:127], v[16:31]
